# adds hand-written prologue phase (weight conversion items with the next item's loads in flight, row conversion loops double-buffered) and hand-written final RMSNorm pass
# speedup vs baseline: 1.0574x; 1.0152x over previous
.LBB0_6:
	s_or_b64 exec, exec, s[6:7]
	s_lshr_b32 s3, s3, 6
	s_lshl_b32 s33, s2, 3
	s_lshl_b32 s34, s46, 3
	s_add_i32 s42, s3, s33
	s_load_dwordx16 s[48:63], s[0:1], 0x48
	s_load_dwordx16 s[64:79], s[0:1], 0xa0
	s_load_dwordx8 s[8:15], s[0:1], 0xe0
	s_load_dwordx2 s[16:17], s[0:1], 0x100
	v_and_b32_e32 v1, 63, v206
	v_lshrrev_b32_e32 v2, 3, v1
	v_and_b32_e32 v3, 7, v1
	s_lshl_b32 s92, s3, 14
	v_mov_b32_e32 v7, 33
	v_mul_u32_u24_e32 v4, v2, v7
	v_lshl_add_u32 v4, v3, 2, v4
	v_lshlrev_b32_e32 v4, 2, v4
	v_add_u32_e32 v4, s92, v4
	v_mov_b32_e32 v7, 0x108
	v_mul_u32_u24_e32 v5, v3, v7
	v_add_u32_e32 v5, v5, v2
	v_lshlrev_b32_e32 v5, 2, v5
	v_add_u32_e32 v5, s92, v5
	v_lshlrev_b32_e32 v6, 5, v3
	s_add_u32 s87, s33, s3
	s_waitcnt lgkmcnt(0)
	s_cmp_ge_u32 s87, 0x3800
	s_cbranch_scc1 .Lp0_items_done
	s_cmp_lt_u32 s87, 0xb00
	s_cbranch_scc1 .Lp0_da_0
	s_cmp_lt_u32 s87, 0x1080
	s_cbranch_scc1 .Lp0_da_1
	s_cmp_lt_u32 s87, 0x1b80
	s_cbranch_scc1 .Lp0_da_2
	s_cmp_lt_u32 s87, 0x1c80
	s_cbranch_scc1 .Lp0_da_3
	s_cmp_lt_u32 s87, 0x1d80
	s_cbranch_scc1 .Lp0_da_4
	s_cmp_lt_u32 s87, 0x1f80
	s_cbranch_scc1 .Lp0_da_5
	s_cmp_lt_u32 s87, 0x2180
	s_cbranch_scc1 .Lp0_da_6
	s_cmp_lt_u32 s87, 0x2380
	s_cbranch_scc1 .Lp0_da_7
	s_cmp_lt_u32 s87, 0x2780
	s_cbranch_scc1 .Lp0_da_8
	s_cmp_lt_u32 s87, 0x3280
	s_cbranch_scc1 .Lp0_da_9
	s_sub_u32 s89, s87, 0x3280
	s_lshr_b32 s90, s89, 5
	s_and_b32 s91, s89, 31
	s_lshl_b32 s92, s91, 7
	s_mul_i32 s93, s90, 0x40000
	s_add_u32 s92, s92, s93
	s_add_u32 s20, s16, s92
	s_addc_u32 s21, s17, 0
	s_mul_i32 s92, s91, 0x2c000
	s_lshl_b32 s93, s90, 7
	s_add_u32 s92, s92, s93
	s_add_u32 s26, s38, s92
	s_addc_u32 s27, s39, 0
	s_add_u32 s26, s26, 0x3700000
	s_addc_u32 s27, s27, 0
	s_mov_b32 s22, 0x1000
	s_mov_b32 s28, 0x1600
	s_mov_b32 s23, 0
	s_branch .Lp0_dda
.Lp0_da_9:
	s_sub_u32 s89, s87, 0x2780
	s_mul_hi_u32 s90, s89, 0x1745d18
	s_mul_i32 s92, s90, 0xb0
	s_sub_u32 s91, s89, s92
	s_and_b32 s92, s91, 7
	s_cmp_lt_u32 s92, 4
	s_cselect_b32 s20, s12, s14
	s_cselect_b32 s21, s13, s15
	s_and_b32 s92, s91, 3
	s_lshl_b32 s92, s92, 7
	s_lshr_b32 s93, s91, 3
	s_lshl_b32 s93, s93, 9
	s_add_u32 s92, s92, s93
	s_mul_i32 s93, s90, 0xb0000
	s_add_u32 s92, s92, s93
	s_add_u32 s20, s20, s92
	s_addc_u32 s21, s21, 0
	s_mul_i32 s92, s91, 0x10000
	s_lshl_b32 s93, s90, 7
	s_add_u32 s92, s92, s93
	s_add_u32 s26, s38, s92
	s_addc_u32 s27, s39, 0
	s_add_u32 s26, s26, 0x2b00000
	s_addc_u32 s27, s27, 0
	s_mov_b32 s22, 0x2c00
	s_mov_b32 s28, 0x800
	s_lshl_b32 s93, s90, 8
	s_add_u32 s24, s10, s93
	s_addc_u32 s25, s11, 0
	s_mov_b32 s23, 1
	s_branch .Lp0_dda
.Lp0_da_8:
	s_sub_u32 s89, s87, 0x2380
	s_lshr_b32 s90, s89, 6
	s_and_b32 s91, s89, 63
	s_cmp_lt_u32 s91, 32
	s_cselect_b32 s20, s76, s78
	s_cselect_b32 s21, s77, s79
	s_and_b32 s92, s91, 31
	s_lshl_b32 s92, s92, 7
	s_mul_i32 s93, s90, 0x40000
	s_add_u32 s92, s92, s93
	s_add_u32 s20, s20, s92
	s_addc_u32 s21, s21, 0
	s_mul_i32 s92, s91, 0x10000
	s_lshl_b32 s93, s90, 7
	s_add_u32 s92, s92, s93
	s_add_u32 s26, s38, s92
	s_addc_u32 s27, s39, 0
	s_add_u32 s26, s26, 0x2700000
	s_addc_u32 s27, s27, 0
	s_mov_b32 s22, 0x1000
	s_mov_b32 s28, 0x800
	s_lshl_b32 s93, s90, 8
	s_add_u32 s24, s72, s93
	s_addc_u32 s25, s73, 0
	s_mov_b32 s23, 1
	s_branch .Lp0_dda
.Lp0_da_7:
	s_sub_u32 s89, s87, 0x2180
	s_lshr_b32 s90, s89, 5
	s_and_b32 s91, s89, 31
	s_lshl_b32 s92, s91, 7
	s_mul_i32 s93, s90, 0x40000
	s_add_u32 s92, s92, s93
	s_add_u32 s20, s8, s92
	s_addc_u32 s21, s9, 0
	s_mul_i32 s92, s91, 0x10000
	s_lshl_b32 s93, s90, 7
	s_add_u32 s92, s92, s93
	s_add_u32 s26, s38, s92
	s_addc_u32 s27, s39, 0
	s_add_u32 s26, s26, 0x2500000
	s_addc_u32 s27, s27, 0
	s_mov_b32 s22, 0x1000
	s_mov_b32 s28, 0x800
	s_mov_b32 s23, 0
	s_branch .Lp0_dda
.Lp0_da_6:
	s_sub_u32 s89, s87, 0x1f80
	s_lshr_b32 s90, s89, 5
	s_and_b32 s91, s89, 31
	s_lshl_b32 s92, s91, 7
	s_mul_i32 s93, s90, 0x40000
	s_add_u32 s92, s92, s93
	s_add_u32 s20, s74, s92
	s_addc_u32 s21, s75, 0
	s_mul_i32 s92, s91, 0x10000
	s_lshl_b32 s93, s90, 7
	s_add_u32 s92, s92, s93
	s_add_u32 s26, s38, s92
	s_addc_u32 s27, s39, 0
	s_add_u32 s26, s26, 0x2300000
	s_addc_u32 s27, s27, 0
	s_mov_b32 s22, 0x1000
	s_mov_b32 s28, 0x800
	s_lshl_b32 s93, s90, 8
	s_add_u32 s24, s70, s93
	s_addc_u32 s25, s71, 0
	s_mov_b32 s23, 1
	s_branch .Lp0_dda
.Lp0_da_5:
	s_sub_u32 s89, s87, 0x1d80
	s_lshr_b32 s90, s89, 5
	s_and_b32 s91, s89, 31
	s_lshl_b32 s92, s91, 7
	s_mul_i32 s93, s90, 0x40000
	s_add_u32 s92, s92, s93
	s_add_u32 s20, s68, s92
	s_addc_u32 s21, s69, 0
	s_mul_i32 s92, s91, 0x10000
	s_lshl_b32 s93, s90, 7
	s_add_u32 s92, s92, s93
	s_add_u32 s26, s38, s92
	s_addc_u32 s27, s39, 0
	s_add_u32 s26, s26, 0x2100000
	s_addc_u32 s27, s27, 0
	s_mov_b32 s22, 0x1000
	s_mov_b32 s28, 0x800
	s_mov_b32 s23, 0
	s_branch .Lp0_dda
.Lp0_da_4:
	s_sub_u32 s89, s87, 0x1c80
	s_lshr_b32 s90, s89, 5
	s_and_b32 s91, s89, 31
	s_lshl_b32 s92, s91, 7
	s_mul_i32 s93, s90, 0x40000
	s_add_u32 s92, s92, s93
	s_add_u32 s20, s66, s92
	s_addc_u32 s21, s67, 0
	s_mul_i32 s92, s91, 0x8000
	s_lshl_b32 s93, s90, 7
	s_add_u32 s92, s92, s93
	s_add_u32 s26, s38, s92
	s_addc_u32 s27, s39, 0
	s_add_u32 s26, s26, 0x2000000
	s_addc_u32 s27, s27, 0
	s_mov_b32 s22, 0x1000
	s_mov_b32 s28, 0x400
	s_mov_b32 s23, 0
	s_branch .Lp0_dda
.Lp0_da_3:
	s_sub_u32 s89, s87, 0x1b80
	s_lshr_b32 s90, s89, 5
	s_and_b32 s91, s89, 31
	s_lshl_b32 s92, s91, 7
	s_mul_i32 s93, s90, 0x40000
	s_add_u32 s92, s92, s93
	s_add_u32 s20, s64, s92
	s_addc_u32 s21, s65, 0
	s_mul_i32 s92, s91, 0x8000
	s_lshl_b32 s93, s90, 7
	s_add_u32 s92, s92, s93
	s_add_u32 s26, s38, s92
	s_addc_u32 s27, s39, 0
	s_add_u32 s26, s26, 0x1f00000
	s_addc_u32 s27, s27, 0
	s_mov_b32 s22, 0x1000
	s_mov_b32 s28, 0x400
	s_mov_b32 s23, 0
	s_branch .Lp0_dda
.Lp0_da_2:
	s_sub_u32 s89, s87, 0x1080
	s_mul_hi_u32 s90, s89, 0x1745d18
	s_mul_i32 s92, s90, 0xb0
	s_sub_u32 s91, s89, s92
	s_lshl_b32 s92, s91, 5
	s_add_u32 s93, s92, 8
	s_cmp_lt_u32 s92, 0xe00
	s_cselect_b32 s92, s92, s93
	s_lshl_b32 s92, s92, 2
	s_mul_i32 s93, s90, 0x160800
	s_add_u32 s92, s92, s93
	s_add_u32 s20, s58, s92
	s_addc_u32 s21, s59, 0
	s_mul_i32 s92, s91, 0x10000
	s_lshl_b32 s93, s90, 7
	s_add_u32 s92, s92, s93
	s_add_u32 s26, s38, s92
	s_addc_u32 s27, s39, 0
	s_add_u32 s26, s26, 0x1300000
	s_addc_u32 s27, s27, 0
	s_mov_b32 s22, 0x5820
	s_mov_b32 s28, 0x800
	s_lshl_b32 s93, s90, 8
	s_add_u32 s24, s56, s93
	s_addc_u32 s25, s57, 0
	s_mov_b32 s23, 1
	s_branch .Lp0_dda
.Lp0_da_1:
	s_sub_u32 s89, s87, 0xb00
	s_lshr_b32 s90, s89, 5
	s_and_b32 s91, s89, 31
	s_lshl_b32 s92, s91, 7
	s_mul_i32 s93, s90, 0x40000
	s_add_u32 s92, s92, s93
	s_add_u32 s20, s54, s92
	s_addc_u32 s21, s55, 0
	s_mul_i32 s92, s91, 0x2c000
	s_lshl_b32 s93, s90, 7
	s_add_u32 s92, s92, s93
	s_add_u32 s26, s38, s92
	s_addc_u32 s27, s39, 0
	s_add_u32 s26, s26, 0xd00000
	s_addc_u32 s27, s27, 0
	s_mov_b32 s22, 0x1000
	s_mov_b32 s28, 0x1600
	s_mov_b32 s23, 0
	s_branch .Lp0_dda
.Lp0_da_0:
	s_sub_u32 s89, s87, 0
	s_mul_hi_u32 s90, s89, 0x1745d18
	s_mul_i32 s92, s90, 0xb0
	s_sub_u32 s91, s89, s92
	s_and_b32 s92, s91, 7
	s_cmp_lt_u32 s92, 4
	s_cselect_b32 s20, s50, s52
	s_cselect_b32 s21, s51, s53
	s_and_b32 s92, s91, 3
	s_lshl_b32 s92, s92, 7
	s_lshr_b32 s93, s91, 3
	s_lshl_b32 s93, s93, 9
	s_add_u32 s92, s92, s93
	s_mul_i32 s93, s90, 0xb0000
	s_add_u32 s92, s92, s93
	s_add_u32 s20, s20, s92
	s_addc_u32 s21, s21, 0
	s_mul_i32 s92, s91, 0x10000
	s_lshl_b32 s93, s90, 7
	s_add_u32 s92, s92, s93
	s_add_u32 s26, s38, s92
	s_addc_u32 s27, s39, 0
	s_add_u32 s26, s26, 0x100000
	s_addc_u32 s27, s27, 0
	s_mov_b32 s22, 0x2c00
	s_mov_b32 s28, 0x800
	s_lshl_b32 s93, s90, 8
	s_add_u32 s24, s48, s93
	s_addc_u32 s25, s49, 0
	s_mov_b32 s23, 1
.Lp0_dda:
	v_mov_b32_e32 v7, s22
	v_mul_u32_u24_e32 v10, v2, v7
	v_lshl_add_u32 v10, v3, 4, v10
	v_mov_b32_e32 v7, s28
	v_mul_u32_u24_e32 v11, v2, v7
	v_lshl_add_u32 v11, v3, 4, v11
	s_lshl_b32 s92, s22, 3
	global_load_dwordx4 v[32:35], v10, s[20:21]
	s_add_u32 s20, s20, s92
	s_addc_u32 s21, s21, 0
	global_load_dwordx4 v[36:39], v10, s[20:21]
	s_add_u32 s20, s20, s92
	s_addc_u32 s21, s21, 0
	global_load_dwordx4 v[40:43], v10, s[20:21]
	s_add_u32 s20, s20, s92
	s_addc_u32 s21, s21, 0
	global_load_dwordx4 v[44:47], v10, s[20:21]
	s_add_u32 s20, s20, s92
	s_addc_u32 s21, s21, 0
	global_load_dwordx4 v[48:51], v10, s[20:21]
	s_add_u32 s20, s20, s92
	s_addc_u32 s21, s21, 0
	global_load_dwordx4 v[52:55], v10, s[20:21]
	s_add_u32 s20, s20, s92
	s_addc_u32 s21, s21, 0
	global_load_dwordx4 v[56:59], v10, s[20:21]
	s_add_u32 s20, s20, s92
	s_addc_u32 s21, s21, 0
	global_load_dwordx4 v[60:63], v10, s[20:21]
	s_cmp_eq_u32 s23, 0
	s_cbranch_scc1 .Lp0_nga
	global_load_dwordx4 v[64:67], v6, s[24:25]
	global_load_dwordx4 v[68:71], v6, s[24:25] offset:16
	s_branch .Lp0_gda
.Lp0_nga:
	v_mov_b32_e32 v64, 1.0
	v_mov_b32_e32 v65, 1.0
	v_mov_b32_e32 v66, 1.0
	v_mov_b32_e32 v67, 1.0
	v_mov_b32_e32 v68, 1.0
	v_mov_b32_e32 v69, 1.0
	v_mov_b32_e32 v70, 1.0
	v_mov_b32_e32 v71, 1.0
.Lp0_gda:
.Lp0_iloop:
	s_add_u32 s88, s87, s34
	s_cmp_ge_u32 s88, 0x3800
	s_cbranch_scc1 .Lp0_ilast0
	s_cmp_lt_u32 s88, 0xb00
	s_cbranch_scc1 .Lp0_dn0_0
	s_cmp_lt_u32 s88, 0x1080
	s_cbranch_scc1 .Lp0_dn0_1
	s_cmp_lt_u32 s88, 0x1b80
	s_cbranch_scc1 .Lp0_dn0_2
	s_cmp_lt_u32 s88, 0x1c80
	s_cbranch_scc1 .Lp0_dn0_3
	s_cmp_lt_u32 s88, 0x1d80
	s_cbranch_scc1 .Lp0_dn0_4
	s_cmp_lt_u32 s88, 0x1f80
	s_cbranch_scc1 .Lp0_dn0_5
	s_cmp_lt_u32 s88, 0x2180
	s_cbranch_scc1 .Lp0_dn0_6
	s_cmp_lt_u32 s88, 0x2380
	s_cbranch_scc1 .Lp0_dn0_7
	s_cmp_lt_u32 s88, 0x2780
	s_cbranch_scc1 .Lp0_dn0_8
	s_cmp_lt_u32 s88, 0x3280
	s_cbranch_scc1 .Lp0_dn0_9
	s_sub_u32 s89, s88, 0x3280
	s_lshr_b32 s90, s89, 5
	s_and_b32 s91, s89, 31
	s_lshl_b32 s92, s91, 7
	s_mul_i32 s93, s90, 0x40000
	s_add_u32 s92, s92, s93
	s_add_u32 s60, s16, s92
	s_addc_u32 s61, s17, 0
	s_mul_i32 s92, s91, 0x2c000
	s_lshl_b32 s93, s90, 7
	s_add_u32 s92, s92, s93
	s_add_u32 s82, s38, s92
	s_addc_u32 s83, s39, 0
	s_add_u32 s82, s82, 0x3700000
	s_addc_u32 s83, s83, 0
	s_mov_b32 s62, 0x1000
	s_mov_b32 s86, 0x1600
	s_mov_b32 s63, 0
	s_branch .Lp0_ddn0
.Lp0_dn0_9:
	s_sub_u32 s89, s88, 0x2780
	s_mul_hi_u32 s90, s89, 0x1745d18
	s_mul_i32 s92, s90, 0xb0
	s_sub_u32 s91, s89, s92
	s_and_b32 s92, s91, 7
	s_cmp_lt_u32 s92, 4
	s_cselect_b32 s60, s12, s14
	s_cselect_b32 s61, s13, s15
	s_and_b32 s92, s91, 3
	s_lshl_b32 s92, s92, 7
	s_lshr_b32 s93, s91, 3
	s_lshl_b32 s93, s93, 9
	s_add_u32 s92, s92, s93
	s_mul_i32 s93, s90, 0xb0000
	s_add_u32 s92, s92, s93
	s_add_u32 s60, s60, s92
	s_addc_u32 s61, s61, 0
	s_mul_i32 s92, s91, 0x10000
	s_lshl_b32 s93, s90, 7
	s_add_u32 s92, s92, s93
	s_add_u32 s82, s38, s92
	s_addc_u32 s83, s39, 0
	s_add_u32 s82, s82, 0x2b00000
	s_addc_u32 s83, s83, 0
	s_mov_b32 s62, 0x2c00
	s_mov_b32 s86, 0x800
	s_lshl_b32 s93, s90, 8
	s_add_u32 s80, s10, s93
	s_addc_u32 s81, s11, 0
	s_mov_b32 s63, 1
	s_branch .Lp0_ddn0
.Lp0_dn0_8:
	s_sub_u32 s89, s88, 0x2380
	s_lshr_b32 s90, s89, 6
	s_and_b32 s91, s89, 63
	s_cmp_lt_u32 s91, 32
	s_cselect_b32 s60, s76, s78
	s_cselect_b32 s61, s77, s79
	s_and_b32 s92, s91, 31
	s_lshl_b32 s92, s92, 7
	s_mul_i32 s93, s90, 0x40000
	s_add_u32 s92, s92, s93
	s_add_u32 s60, s60, s92
	s_addc_u32 s61, s61, 0
	s_mul_i32 s92, s91, 0x10000
	s_lshl_b32 s93, s90, 7
	s_add_u32 s92, s92, s93
	s_add_u32 s82, s38, s92
	s_addc_u32 s83, s39, 0
	s_add_u32 s82, s82, 0x2700000
	s_addc_u32 s83, s83, 0
	s_mov_b32 s62, 0x1000
	s_mov_b32 s86, 0x800
	s_lshl_b32 s93, s90, 8
	s_add_u32 s80, s72, s93
	s_addc_u32 s81, s73, 0
	s_mov_b32 s63, 1
	s_branch .Lp0_ddn0
.Lp0_dn0_7:
	s_sub_u32 s89, s88, 0x2180
	s_lshr_b32 s90, s89, 5
	s_and_b32 s91, s89, 31
	s_lshl_b32 s92, s91, 7
	s_mul_i32 s93, s90, 0x40000
	s_add_u32 s92, s92, s93
	s_add_u32 s60, s8, s92
	s_addc_u32 s61, s9, 0
	s_mul_i32 s92, s91, 0x10000
	s_lshl_b32 s93, s90, 7
	s_add_u32 s92, s92, s93
	s_add_u32 s82, s38, s92
	s_addc_u32 s83, s39, 0
	s_add_u32 s82, s82, 0x2500000
	s_addc_u32 s83, s83, 0
	s_mov_b32 s62, 0x1000
	s_mov_b32 s86, 0x800
	s_mov_b32 s63, 0
	s_branch .Lp0_ddn0
.Lp0_dn0_6:
	s_sub_u32 s89, s88, 0x1f80
	s_lshr_b32 s90, s89, 5
	s_and_b32 s91, s89, 31
	s_lshl_b32 s92, s91, 7
	s_mul_i32 s93, s90, 0x40000
	s_add_u32 s92, s92, s93
	s_add_u32 s60, s74, s92
	s_addc_u32 s61, s75, 0
	s_mul_i32 s92, s91, 0x10000
	s_lshl_b32 s93, s90, 7
	s_add_u32 s92, s92, s93
	s_add_u32 s82, s38, s92
	s_addc_u32 s83, s39, 0
	s_add_u32 s82, s82, 0x2300000
	s_addc_u32 s83, s83, 0
	s_mov_b32 s62, 0x1000
	s_mov_b32 s86, 0x800
	s_lshl_b32 s93, s90, 8
	s_add_u32 s80, s70, s93
	s_addc_u32 s81, s71, 0
	s_mov_b32 s63, 1
	s_branch .Lp0_ddn0
.Lp0_dn0_5:
	s_sub_u32 s89, s88, 0x1d80
	s_lshr_b32 s90, s89, 5
	s_and_b32 s91, s89, 31
	s_lshl_b32 s92, s91, 7
	s_mul_i32 s93, s90, 0x40000
	s_add_u32 s92, s92, s93
	s_add_u32 s60, s68, s92
	s_addc_u32 s61, s69, 0
	s_mul_i32 s92, s91, 0x10000
	s_lshl_b32 s93, s90, 7
	s_add_u32 s92, s92, s93
	s_add_u32 s82, s38, s92
	s_addc_u32 s83, s39, 0
	s_add_u32 s82, s82, 0x2100000
	s_addc_u32 s83, s83, 0
	s_mov_b32 s62, 0x1000
	s_mov_b32 s86, 0x800
	s_mov_b32 s63, 0
	s_branch .Lp0_ddn0
.Lp0_dn0_4:
	s_sub_u32 s89, s88, 0x1c80
	s_lshr_b32 s90, s89, 5
	s_and_b32 s91, s89, 31
	s_lshl_b32 s92, s91, 7
	s_mul_i32 s93, s90, 0x40000
	s_add_u32 s92, s92, s93
	s_add_u32 s60, s66, s92
	s_addc_u32 s61, s67, 0
	s_mul_i32 s92, s91, 0x8000
	s_lshl_b32 s93, s90, 7
	s_add_u32 s92, s92, s93
	s_add_u32 s82, s38, s92
	s_addc_u32 s83, s39, 0
	s_add_u32 s82, s82, 0x2000000
	s_addc_u32 s83, s83, 0
	s_mov_b32 s62, 0x1000
	s_mov_b32 s86, 0x400
	s_mov_b32 s63, 0
	s_branch .Lp0_ddn0
.Lp0_dn0_3:
	s_sub_u32 s89, s88, 0x1b80
	s_lshr_b32 s90, s89, 5
	s_and_b32 s91, s89, 31
	s_lshl_b32 s92, s91, 7
	s_mul_i32 s93, s90, 0x40000
	s_add_u32 s92, s92, s93
	s_add_u32 s60, s64, s92
	s_addc_u32 s61, s65, 0
	s_mul_i32 s92, s91, 0x8000
	s_lshl_b32 s93, s90, 7
	s_add_u32 s92, s92, s93
	s_add_u32 s82, s38, s92
	s_addc_u32 s83, s39, 0
	s_add_u32 s82, s82, 0x1f00000
	s_addc_u32 s83, s83, 0
	s_mov_b32 s62, 0x1000
	s_mov_b32 s86, 0x400
	s_mov_b32 s63, 0
	s_branch .Lp0_ddn0
.Lp0_dn0_2:
	s_sub_u32 s89, s88, 0x1080
	s_mul_hi_u32 s90, s89, 0x1745d18
	s_mul_i32 s92, s90, 0xb0
	s_sub_u32 s91, s89, s92
	s_lshl_b32 s92, s91, 5
	s_add_u32 s93, s92, 8
	s_cmp_lt_u32 s92, 0xe00
	s_cselect_b32 s92, s92, s93
	s_lshl_b32 s92, s92, 2
	s_mul_i32 s93, s90, 0x160800
	s_add_u32 s92, s92, s93
	s_add_u32 s60, s58, s92
	s_addc_u32 s61, s59, 0
	s_mul_i32 s92, s91, 0x10000
	s_lshl_b32 s93, s90, 7
	s_add_u32 s92, s92, s93
	s_add_u32 s82, s38, s92
	s_addc_u32 s83, s39, 0
	s_add_u32 s82, s82, 0x1300000
	s_addc_u32 s83, s83, 0
	s_mov_b32 s62, 0x5820
	s_mov_b32 s86, 0x800
	s_lshl_b32 s93, s90, 8
	s_add_u32 s80, s56, s93
	s_addc_u32 s81, s57, 0
	s_mov_b32 s63, 1
	s_branch .Lp0_ddn0
.Lp0_dn0_1:
	s_sub_u32 s89, s88, 0xb00
	s_lshr_b32 s90, s89, 5
	s_and_b32 s91, s89, 31
	s_lshl_b32 s92, s91, 7
	s_mul_i32 s93, s90, 0x40000
	s_add_u32 s92, s92, s93
	s_add_u32 s60, s54, s92
	s_addc_u32 s61, s55, 0
	s_mul_i32 s92, s91, 0x2c000
	s_lshl_b32 s93, s90, 7
	s_add_u32 s92, s92, s93
	s_add_u32 s82, s38, s92
	s_addc_u32 s83, s39, 0
	s_add_u32 s82, s82, 0xd00000
	s_addc_u32 s83, s83, 0
	s_mov_b32 s62, 0x1000
	s_mov_b32 s86, 0x1600
	s_mov_b32 s63, 0
	s_branch .Lp0_ddn0
.Lp0_dn0_0:
	s_sub_u32 s89, s88, 0
	s_mul_hi_u32 s90, s89, 0x1745d18
	s_mul_i32 s92, s90, 0xb0
	s_sub_u32 s91, s89, s92
	s_and_b32 s92, s91, 7
	s_cmp_lt_u32 s92, 4
	s_cselect_b32 s60, s50, s52
	s_cselect_b32 s61, s51, s53
	s_and_b32 s92, s91, 3
	s_lshl_b32 s92, s92, 7
	s_lshr_b32 s93, s91, 3
	s_lshl_b32 s93, s93, 9
	s_add_u32 s92, s92, s93
	s_mul_i32 s93, s90, 0xb0000
	s_add_u32 s92, s92, s93
	s_add_u32 s60, s60, s92
	s_addc_u32 s61, s61, 0
	s_mul_i32 s92, s91, 0x10000
	s_lshl_b32 s93, s90, 7
	s_add_u32 s92, s92, s93
	s_add_u32 s82, s38, s92
	s_addc_u32 s83, s39, 0
	s_add_u32 s82, s82, 0x100000
	s_addc_u32 s83, s83, 0
	s_mov_b32 s62, 0x2c00
	s_mov_b32 s86, 0x800
	s_lshl_b32 s93, s90, 8
	s_add_u32 s80, s48, s93
	s_addc_u32 s81, s49, 0
	s_mov_b32 s63, 1
.Lp0_ddn0:
	v_mov_b32_e32 v7, s62
	v_mul_u32_u24_e32 v12, v2, v7
	v_lshl_add_u32 v12, v3, 4, v12
	v_mov_b32_e32 v7, s86
	v_mul_u32_u24_e32 v13, v2, v7
	v_lshl_add_u32 v13, v3, 4, v13
	s_lshl_b32 s92, s62, 3
	global_load_dwordx4 v[72:75], v12, s[60:61]
	s_add_u32 s60, s60, s92
	s_addc_u32 s61, s61, 0
	global_load_dwordx4 v[76:79], v12, s[60:61]
	s_add_u32 s60, s60, s92
	s_addc_u32 s61, s61, 0
	global_load_dwordx4 v[80:83], v12, s[60:61]
	s_add_u32 s60, s60, s92
	s_addc_u32 s61, s61, 0
	global_load_dwordx4 v[84:87], v12, s[60:61]
	s_add_u32 s60, s60, s92
	s_addc_u32 s61, s61, 0
	global_load_dwordx4 v[88:91], v12, s[60:61]
	s_add_u32 s60, s60, s92
	s_addc_u32 s61, s61, 0
	global_load_dwordx4 v[92:95], v12, s[60:61]
	s_add_u32 s60, s60, s92
	s_addc_u32 s61, s61, 0
	global_load_dwordx4 v[96:99], v12, s[60:61]
	s_add_u32 s60, s60, s92
	s_addc_u32 s61, s61, 0
	global_load_dwordx4 v[100:103], v12, s[60:61]
	s_cmp_eq_u32 s63, 0
	s_cbranch_scc1 .Lp0_ngn0
	global_load_dwordx4 v[104:107], v6, s[80:81]
	global_load_dwordx4 v[108:111], v6, s[80:81] offset:16
	s_branch .Lp0_gdn0
.Lp0_ngn0:
	v_mov_b32_e32 v104, 1.0
	v_mov_b32_e32 v105, 1.0
	v_mov_b32_e32 v106, 1.0
	v_mov_b32_e32 v107, 1.0
	v_mov_b32_e32 v108, 1.0
	v_mov_b32_e32 v109, 1.0
	v_mov_b32_e32 v110, 1.0
	v_mov_b32_e32 v111, 1.0
.Lp0_gdn0:
	s_waitcnt vmcnt(8)
	ds_write_b32 v4, v32
	ds_write_b32 v4, v33 offset:4
	ds_write_b32 v4, v34 offset:8
	ds_write_b32 v4, v35 offset:12
	ds_write_b32 v4, v36 offset:1056
	ds_write_b32 v4, v37 offset:1060
	ds_write_b32 v4, v38 offset:1064
	ds_write_b32 v4, v39 offset:1068
	ds_write_b32 v4, v40 offset:2112
	ds_write_b32 v4, v41 offset:2116
	ds_write_b32 v4, v42 offset:2120
	ds_write_b32 v4, v43 offset:2124
	ds_write_b32 v4, v44 offset:3168
	ds_write_b32 v4, v45 offset:3172
	ds_write_b32 v4, v46 offset:3176
	ds_write_b32 v4, v47 offset:3180
	ds_write_b32 v4, v48 offset:4224
	ds_write_b32 v4, v49 offset:4228
	ds_write_b32 v4, v50 offset:4232
	ds_write_b32 v4, v51 offset:4236
	ds_write_b32 v4, v52 offset:5280
	ds_write_b32 v4, v53 offset:5284
	ds_write_b32 v4, v54 offset:5288
	ds_write_b32 v4, v55 offset:5292
	ds_write_b32 v4, v56 offset:6336
	ds_write_b32 v4, v57 offset:6340
	ds_write_b32 v4, v58 offset:6344
	ds_write_b32 v4, v59 offset:6348
	ds_write_b32 v4, v60 offset:7392
	ds_write_b32 v4, v61 offset:7396
	ds_write_b32 v4, v62 offset:7400
	ds_write_b32 v4, v63 offset:7404
	s_waitcnt lgkmcnt(0)
	s_lshl_b32 s92, s28, 3
	ds_read_b32 v32, v5
	ds_read_b32 v33, v5 offset:132
	ds_read_b32 v34, v5 offset:264
	ds_read_b32 v35, v5 offset:396
	ds_read_b32 v36, v5 offset:528
	ds_read_b32 v37, v5 offset:660
	ds_read_b32 v38, v5 offset:792
	ds_read_b32 v39, v5 offset:924
	ds_read_b32 v40, v5 offset:32
	ds_read_b32 v41, v5 offset:164
	ds_read_b32 v42, v5 offset:296
	ds_read_b32 v43, v5 offset:428
	ds_read_b32 v44, v5 offset:560
	ds_read_b32 v45, v5 offset:692
	ds_read_b32 v46, v5 offset:824
	ds_read_b32 v47, v5 offset:956
	s_waitcnt lgkmcnt(8)
	v_mul_f32_e32 v32, v32, v64
	v_mul_f32_e32 v33, v33, v65
	v_mul_f32_e32 v34, v34, v66
	v_mul_f32_e32 v35, v35, v67
	v_mul_f32_e32 v36, v36, v68
	v_mul_f32_e32 v37, v37, v69
	v_mul_f32_e32 v38, v38, v70
	v_mul_f32_e32 v39, v39, v71
	v_cvt_pk_bf16_f32 v32, v32, v33
	v_cvt_pk_bf16_f32 v33, v34, v35
	v_cvt_pk_bf16_f32 v34, v36, v37
	v_cvt_pk_bf16_f32 v35, v38, v39
	global_store_dwordx4 v11, v[32:35], s[26:27]
	s_add_u32 s26, s26, s92
	s_addc_u32 s27, s27, 0
	s_waitcnt lgkmcnt(0)
	v_mul_f32_e32 v40, v40, v64
	v_mul_f32_e32 v41, v41, v65
	v_mul_f32_e32 v42, v42, v66
	v_mul_f32_e32 v43, v43, v67
	v_mul_f32_e32 v44, v44, v68
	v_mul_f32_e32 v45, v45, v69
	v_mul_f32_e32 v46, v46, v70
	v_mul_f32_e32 v47, v47, v71
	v_cvt_pk_bf16_f32 v40, v40, v41
	v_cvt_pk_bf16_f32 v41, v42, v43
	v_cvt_pk_bf16_f32 v42, v44, v45
	v_cvt_pk_bf16_f32 v43, v46, v47
	global_store_dwordx4 v11, v[40:43], s[26:27]
	s_add_u32 s26, s26, s92
	s_addc_u32 s27, s27, 0
	ds_read_b32 v48, v5 offset:64
	ds_read_b32 v49, v5 offset:196
	ds_read_b32 v50, v5 offset:328
	ds_read_b32 v51, v5 offset:460
	ds_read_b32 v52, v5 offset:592
	ds_read_b32 v53, v5 offset:724
	ds_read_b32 v54, v5 offset:856
	ds_read_b32 v55, v5 offset:988
	ds_read_b32 v56, v5 offset:96
	ds_read_b32 v57, v5 offset:228
	ds_read_b32 v58, v5 offset:360
	ds_read_b32 v59, v5 offset:492
	ds_read_b32 v60, v5 offset:624
	ds_read_b32 v61, v5 offset:756
	ds_read_b32 v62, v5 offset:888
	ds_read_b32 v63, v5 offset:1020
	s_waitcnt lgkmcnt(8)
	v_mul_f32_e32 v48, v48, v64
	v_mul_f32_e32 v49, v49, v65
	v_mul_f32_e32 v50, v50, v66
	v_mul_f32_e32 v51, v51, v67
	v_mul_f32_e32 v52, v52, v68
	v_mul_f32_e32 v53, v53, v69
	v_mul_f32_e32 v54, v54, v70
	v_mul_f32_e32 v55, v55, v71
	v_cvt_pk_bf16_f32 v48, v48, v49
	v_cvt_pk_bf16_f32 v49, v50, v51
	v_cvt_pk_bf16_f32 v50, v52, v53
	v_cvt_pk_bf16_f32 v51, v54, v55
	global_store_dwordx4 v11, v[48:51], s[26:27]
	s_add_u32 s26, s26, s92
	s_addc_u32 s27, s27, 0
	s_waitcnt lgkmcnt(0)
	v_mul_f32_e32 v56, v56, v64
	v_mul_f32_e32 v57, v57, v65
	v_mul_f32_e32 v58, v58, v66
	v_mul_f32_e32 v59, v59, v67
	v_mul_f32_e32 v60, v60, v68
	v_mul_f32_e32 v61, v61, v69
	v_mul_f32_e32 v62, v62, v70
	v_mul_f32_e32 v63, v63, v71
	v_cvt_pk_bf16_f32 v56, v56, v57
	v_cvt_pk_bf16_f32 v57, v58, v59
	v_cvt_pk_bf16_f32 v58, v60, v61
	v_cvt_pk_bf16_f32 v59, v62, v63
	global_store_dwordx4 v11, v[56:59], s[26:27]
	s_mov_b32 s87, s88
	s_add_u32 s88, s87, s34
	s_cmp_ge_u32 s88, 0x3800
	s_cbranch_scc1 .Lp0_ilast1
	s_cmp_lt_u32 s88, 0xb00
	s_cbranch_scc1 .Lp0_dn1_0
	s_cmp_lt_u32 s88, 0x1080
	s_cbranch_scc1 .Lp0_dn1_1
	s_cmp_lt_u32 s88, 0x1b80
	s_cbranch_scc1 .Lp0_dn1_2
	s_cmp_lt_u32 s88, 0x1c80
	s_cbranch_scc1 .Lp0_dn1_3
	s_cmp_lt_u32 s88, 0x1d80
	s_cbranch_scc1 .Lp0_dn1_4
	s_cmp_lt_u32 s88, 0x1f80
	s_cbranch_scc1 .Lp0_dn1_5
	s_cmp_lt_u32 s88, 0x2180
	s_cbranch_scc1 .Lp0_dn1_6
	s_cmp_lt_u32 s88, 0x2380
	s_cbranch_scc1 .Lp0_dn1_7
	s_cmp_lt_u32 s88, 0x2780
	s_cbranch_scc1 .Lp0_dn1_8
	s_cmp_lt_u32 s88, 0x3280
	s_cbranch_scc1 .Lp0_dn1_9
	s_sub_u32 s89, s88, 0x3280
	s_lshr_b32 s90, s89, 5
	s_and_b32 s91, s89, 31
	s_lshl_b32 s92, s91, 7
	s_mul_i32 s93, s90, 0x40000
	s_add_u32 s92, s92, s93
	s_add_u32 s20, s16, s92
	s_addc_u32 s21, s17, 0
	s_mul_i32 s92, s91, 0x2c000
	s_lshl_b32 s93, s90, 7
	s_add_u32 s92, s92, s93
	s_add_u32 s26, s38, s92
	s_addc_u32 s27, s39, 0
	s_add_u32 s26, s26, 0x3700000
	s_addc_u32 s27, s27, 0
	s_mov_b32 s22, 0x1000
	s_mov_b32 s28, 0x1600
	s_mov_b32 s23, 0
	s_branch .Lp0_ddn1
.Lp0_dn1_9:
	s_sub_u32 s89, s88, 0x2780
	s_mul_hi_u32 s90, s89, 0x1745d18
	s_mul_i32 s92, s90, 0xb0
	s_sub_u32 s91, s89, s92
	s_and_b32 s92, s91, 7
	s_cmp_lt_u32 s92, 4
	s_cselect_b32 s20, s12, s14
	s_cselect_b32 s21, s13, s15
	s_and_b32 s92, s91, 3
	s_lshl_b32 s92, s92, 7
	s_lshr_b32 s93, s91, 3
	s_lshl_b32 s93, s93, 9
	s_add_u32 s92, s92, s93
	s_mul_i32 s93, s90, 0xb0000
	s_add_u32 s92, s92, s93
	s_add_u32 s20, s20, s92
	s_addc_u32 s21, s21, 0
	s_mul_i32 s92, s91, 0x10000
	s_lshl_b32 s93, s90, 7
	s_add_u32 s92, s92, s93
	s_add_u32 s26, s38, s92
	s_addc_u32 s27, s39, 0
	s_add_u32 s26, s26, 0x2b00000
	s_addc_u32 s27, s27, 0
	s_mov_b32 s22, 0x2c00
	s_mov_b32 s28, 0x800
	s_lshl_b32 s93, s90, 8
	s_add_u32 s24, s10, s93
	s_addc_u32 s25, s11, 0
	s_mov_b32 s23, 1
	s_branch .Lp0_ddn1
.Lp0_dn1_8:
	s_sub_u32 s89, s88, 0x2380
	s_lshr_b32 s90, s89, 6
	s_and_b32 s91, s89, 63
	s_cmp_lt_u32 s91, 32
	s_cselect_b32 s20, s76, s78
	s_cselect_b32 s21, s77, s79
	s_and_b32 s92, s91, 31
	s_lshl_b32 s92, s92, 7
	s_mul_i32 s93, s90, 0x40000
	s_add_u32 s92, s92, s93
	s_add_u32 s20, s20, s92
	s_addc_u32 s21, s21, 0
	s_mul_i32 s92, s91, 0x10000
	s_lshl_b32 s93, s90, 7
	s_add_u32 s92, s92, s93
	s_add_u32 s26, s38, s92
	s_addc_u32 s27, s39, 0
	s_add_u32 s26, s26, 0x2700000
	s_addc_u32 s27, s27, 0
	s_mov_b32 s22, 0x1000
	s_mov_b32 s28, 0x800
	s_lshl_b32 s93, s90, 8
	s_add_u32 s24, s72, s93
	s_addc_u32 s25, s73, 0
	s_mov_b32 s23, 1
	s_branch .Lp0_ddn1
.Lp0_dn1_7:
	s_sub_u32 s89, s88, 0x2180
	s_lshr_b32 s90, s89, 5
	s_and_b32 s91, s89, 31
	s_lshl_b32 s92, s91, 7
	s_mul_i32 s93, s90, 0x40000
	s_add_u32 s92, s92, s93
	s_add_u32 s20, s8, s92
	s_addc_u32 s21, s9, 0
	s_mul_i32 s92, s91, 0x10000
	s_lshl_b32 s93, s90, 7
	s_add_u32 s92, s92, s93
	s_add_u32 s26, s38, s92
	s_addc_u32 s27, s39, 0
	s_add_u32 s26, s26, 0x2500000
	s_addc_u32 s27, s27, 0
	s_mov_b32 s22, 0x1000
	s_mov_b32 s28, 0x800
	s_mov_b32 s23, 0
	s_branch .Lp0_ddn1
.Lp0_dn1_6:
	s_sub_u32 s89, s88, 0x1f80
	s_lshr_b32 s90, s89, 5
	s_and_b32 s91, s89, 31
	s_lshl_b32 s92, s91, 7
	s_mul_i32 s93, s90, 0x40000
	s_add_u32 s92, s92, s93
	s_add_u32 s20, s74, s92
	s_addc_u32 s21, s75, 0
	s_mul_i32 s92, s91, 0x10000
	s_lshl_b32 s93, s90, 7
	s_add_u32 s92, s92, s93
	s_add_u32 s26, s38, s92
	s_addc_u32 s27, s39, 0
	s_add_u32 s26, s26, 0x2300000
	s_addc_u32 s27, s27, 0
	s_mov_b32 s22, 0x1000
	s_mov_b32 s28, 0x800
	s_lshl_b32 s93, s90, 8
	s_add_u32 s24, s70, s93
	s_addc_u32 s25, s71, 0
	s_mov_b32 s23, 1
	s_branch .Lp0_ddn1
.Lp0_dn1_5:
	s_sub_u32 s89, s88, 0x1d80
	s_lshr_b32 s90, s89, 5
	s_and_b32 s91, s89, 31
	s_lshl_b32 s92, s91, 7
	s_mul_i32 s93, s90, 0x40000
	s_add_u32 s92, s92, s93
	s_add_u32 s20, s68, s92
	s_addc_u32 s21, s69, 0
	s_mul_i32 s92, s91, 0x10000
	s_lshl_b32 s93, s90, 7
	s_add_u32 s92, s92, s93
	s_add_u32 s26, s38, s92
	s_addc_u32 s27, s39, 0
	s_add_u32 s26, s26, 0x2100000
	s_addc_u32 s27, s27, 0
	s_mov_b32 s22, 0x1000
	s_mov_b32 s28, 0x800
	s_mov_b32 s23, 0
	s_branch .Lp0_ddn1
.Lp0_dn1_4:
	s_sub_u32 s89, s88, 0x1c80
	s_lshr_b32 s90, s89, 5
	s_and_b32 s91, s89, 31
	s_lshl_b32 s92, s91, 7
	s_mul_i32 s93, s90, 0x40000
	s_add_u32 s92, s92, s93
	s_add_u32 s20, s66, s92
	s_addc_u32 s21, s67, 0
	s_mul_i32 s92, s91, 0x8000
	s_lshl_b32 s93, s90, 7
	s_add_u32 s92, s92, s93
	s_add_u32 s26, s38, s92
	s_addc_u32 s27, s39, 0
	s_add_u32 s26, s26, 0x2000000
	s_addc_u32 s27, s27, 0
	s_mov_b32 s22, 0x1000
	s_mov_b32 s28, 0x400
	s_mov_b32 s23, 0
	s_branch .Lp0_ddn1
.Lp0_dn1_3:
	s_sub_u32 s89, s88, 0x1b80
	s_lshr_b32 s90, s89, 5
	s_and_b32 s91, s89, 31
	s_lshl_b32 s92, s91, 7
	s_mul_i32 s93, s90, 0x40000
	s_add_u32 s92, s92, s93
	s_add_u32 s20, s64, s92
	s_addc_u32 s21, s65, 0
	s_mul_i32 s92, s91, 0x8000
	s_lshl_b32 s93, s90, 7
	s_add_u32 s92, s92, s93
	s_add_u32 s26, s38, s92
	s_addc_u32 s27, s39, 0
	s_add_u32 s26, s26, 0x1f00000
	s_addc_u32 s27, s27, 0
	s_mov_b32 s22, 0x1000
	s_mov_b32 s28, 0x400
	s_mov_b32 s23, 0
	s_branch .Lp0_ddn1
.Lp0_dn1_2:
	s_sub_u32 s89, s88, 0x1080
	s_mul_hi_u32 s90, s89, 0x1745d18
	s_mul_i32 s92, s90, 0xb0
	s_sub_u32 s91, s89, s92
	s_lshl_b32 s92, s91, 5
	s_add_u32 s93, s92, 8
	s_cmp_lt_u32 s92, 0xe00
	s_cselect_b32 s92, s92, s93
	s_lshl_b32 s92, s92, 2
	s_mul_i32 s93, s90, 0x160800
	s_add_u32 s92, s92, s93
	s_add_u32 s20, s58, s92
	s_addc_u32 s21, s59, 0
	s_mul_i32 s92, s91, 0x10000
	s_lshl_b32 s93, s90, 7
	s_add_u32 s92, s92, s93
	s_add_u32 s26, s38, s92
	s_addc_u32 s27, s39, 0
	s_add_u32 s26, s26, 0x1300000
	s_addc_u32 s27, s27, 0
	s_mov_b32 s22, 0x5820
	s_mov_b32 s28, 0x800
	s_lshl_b32 s93, s90, 8
	s_add_u32 s24, s56, s93
	s_addc_u32 s25, s57, 0
	s_mov_b32 s23, 1
	s_branch .Lp0_ddn1
.Lp0_dn1_1:
	s_sub_u32 s89, s88, 0xb00
	s_lshr_b32 s90, s89, 5
	s_and_b32 s91, s89, 31
	s_lshl_b32 s92, s91, 7
	s_mul_i32 s93, s90, 0x40000
	s_add_u32 s92, s92, s93
	s_add_u32 s20, s54, s92
	s_addc_u32 s21, s55, 0
	s_mul_i32 s92, s91, 0x2c000
	s_lshl_b32 s93, s90, 7
	s_add_u32 s92, s92, s93
	s_add_u32 s26, s38, s92
	s_addc_u32 s27, s39, 0
	s_add_u32 s26, s26, 0xd00000
	s_addc_u32 s27, s27, 0
	s_mov_b32 s22, 0x1000
	s_mov_b32 s28, 0x1600
	s_mov_b32 s23, 0
	s_branch .Lp0_ddn1
.Lp0_dn1_0:
	s_sub_u32 s89, s88, 0
	s_mul_hi_u32 s90, s89, 0x1745d18
	s_mul_i32 s92, s90, 0xb0
	s_sub_u32 s91, s89, s92
	s_and_b32 s92, s91, 7
	s_cmp_lt_u32 s92, 4
	s_cselect_b32 s20, s50, s52
	s_cselect_b32 s21, s51, s53
	s_and_b32 s92, s91, 3
	s_lshl_b32 s92, s92, 7
	s_lshr_b32 s93, s91, 3
	s_lshl_b32 s93, s93, 9
	s_add_u32 s92, s92, s93
	s_mul_i32 s93, s90, 0xb0000
	s_add_u32 s92, s92, s93
	s_add_u32 s20, s20, s92
	s_addc_u32 s21, s21, 0
	s_mul_i32 s92, s91, 0x10000
	s_lshl_b32 s93, s90, 7
	s_add_u32 s92, s92, s93
	s_add_u32 s26, s38, s92
	s_addc_u32 s27, s39, 0
	s_add_u32 s26, s26, 0x100000
	s_addc_u32 s27, s27, 0
	s_mov_b32 s22, 0x2c00
	s_mov_b32 s28, 0x800
	s_lshl_b32 s93, s90, 8
	s_add_u32 s24, s48, s93
	s_addc_u32 s25, s49, 0
	s_mov_b32 s23, 1

.Lp0_gdn1:
	s_waitcnt vmcnt(8)
	ds_write_b32 v4, v72
	ds_write_b32 v4, v73 offset:4
	ds_write_b32 v4, v74 offset:8
	ds_write_b32 v4, v75 offset:12
	ds_write_b32 v4, v76 offset:1056
	ds_write_b32 v4, v77 offset:1060
	ds_write_b32 v4, v78 offset:1064
	ds_write_b32 v4, v79 offset:1068
	ds_write_b32 v4, v80 offset:2112
	ds_write_b32 v4, v81 offset:2116
	ds_write_b32 v4, v82 offset:2120
	ds_write_b32 v4, v83 offset:2124
	ds_write_b32 v4, v84 offset:3168
	ds_write_b32 v4, v85 offset:3172
	ds_write_b32 v4, v86 offset:3176
	ds_write_b32 v4, v87 offset:3180
	ds_write_b32 v4, v88 offset:4224
	ds_write_b32 v4, v89 offset:4228
	ds_write_b32 v4, v90 offset:4232
	ds_write_b32 v4, v91 offset:4236
	ds_write_b32 v4, v92 offset:5280
	ds_write_b32 v4, v93 offset:5284
	ds_write_b32 v4, v94 offset:5288
	ds_write_b32 v4, v95 offset:5292
	ds_write_b32 v4, v96 offset:6336
	ds_write_b32 v4, v97 offset:6340
	ds_write_b32 v4, v98 offset:6344
	ds_write_b32 v4, v99 offset:6348
	ds_write_b32 v4, v100 offset:7392
	ds_write_b32 v4, v101 offset:7396
	ds_write_b32 v4, v102 offset:7400
	ds_write_b32 v4, v103 offset:7404
	s_waitcnt lgkmcnt(0)
	s_lshl_b32 s92, s86, 3
	ds_read_b32 v72, v5
	ds_read_b32 v73, v5 offset:132
	ds_read_b32 v74, v5 offset:264
	ds_read_b32 v75, v5 offset:396
	ds_read_b32 v76, v5 offset:528
	ds_read_b32 v77, v5 offset:660
	ds_read_b32 v78, v5 offset:792
	ds_read_b32 v79, v5 offset:924
	ds_read_b32 v80, v5 offset:32
	ds_read_b32 v81, v5 offset:164
	ds_read_b32 v82, v5 offset:296
	ds_read_b32 v83, v5 offset:428
	ds_read_b32 v84, v5 offset:560
	ds_read_b32 v85, v5 offset:692
	ds_read_b32 v86, v5 offset:824
	ds_read_b32 v87, v5 offset:956
	s_waitcnt lgkmcnt(8)
	v_mul_f32_e32 v72, v72, v104
	v_mul_f32_e32 v73, v73, v105
	v_mul_f32_e32 v74, v74, v106
	v_mul_f32_e32 v75, v75, v107
	v_mul_f32_e32 v76, v76, v108
	v_mul_f32_e32 v77, v77, v109
	v_mul_f32_e32 v78, v78, v110
	v_mul_f32_e32 v79, v79, v111
	v_cvt_pk_bf16_f32 v72, v72, v73
	v_cvt_pk_bf16_f32 v73, v74, v75
	v_cvt_pk_bf16_f32 v74, v76, v77
	v_cvt_pk_bf16_f32 v75, v78, v79
	global_store_dwordx4 v13, v[72:75], s[82:83]
	s_add_u32 s82, s82, s92
	s_addc_u32 s83, s83, 0
	s_waitcnt lgkmcnt(0)
	v_mul_f32_e32 v80, v80, v104
	v_mul_f32_e32 v81, v81, v105
	v_mul_f32_e32 v82, v82, v106
	v_mul_f32_e32 v83, v83, v107
	v_mul_f32_e32 v84, v84, v108
	v_mul_f32_e32 v85, v85, v109
	v_mul_f32_e32 v86, v86, v110
	v_mul_f32_e32 v87, v87, v111
	v_cvt_pk_bf16_f32 v80, v80, v81
	v_cvt_pk_bf16_f32 v81, v82, v83
	v_cvt_pk_bf16_f32 v82, v84, v85
	v_cvt_pk_bf16_f32 v83, v86, v87
	global_store_dwordx4 v13, v[80:83], s[82:83]
	s_add_u32 s82, s82, s92
	s_addc_u32 s83, s83, 0
	ds_read_b32 v88, v5 offset:64
	ds_read_b32 v89, v5 offset:196
	ds_read_b32 v90, v5 offset:328
	ds_read_b32 v91, v5 offset:460
	ds_read_b32 v92, v5 offset:592
	ds_read_b32 v93, v5 offset:724
	ds_read_b32 v94, v5 offset:856
	ds_read_b32 v95, v5 offset:988
	ds_read_b32 v96, v5 offset:96
	ds_read_b32 v97, v5 offset:228
	ds_read_b32 v98, v5 offset:360
	ds_read_b32 v99, v5 offset:492
	ds_read_b32 v100, v5 offset:624
	ds_read_b32 v101, v5 offset:756
	ds_read_b32 v102, v5 offset:888
	ds_read_b32 v103, v5 offset:1020
	s_waitcnt lgkmcnt(8)
	v_mul_f32_e32 v88, v88, v104
	v_mul_f32_e32 v89, v89, v105
	v_mul_f32_e32 v90, v90, v106
	v_mul_f32_e32 v91, v91, v107
	v_mul_f32_e32 v92, v92, v108
	v_mul_f32_e32 v93, v93, v109
	v_mul_f32_e32 v94, v94, v110
	v_mul_f32_e32 v95, v95, v111
	v_cvt_pk_bf16_f32 v88, v88, v89
	v_cvt_pk_bf16_f32 v89, v90, v91
	v_cvt_pk_bf16_f32 v90, v92, v93
	v_cvt_pk_bf16_f32 v91, v94, v95
	global_store_dwordx4 v13, v[88:91], s[82:83]
	s_add_u32 s82, s82, s92
	s_addc_u32 s83, s83, 0
	s_waitcnt lgkmcnt(0)
	v_mul_f32_e32 v96, v96, v104
	v_mul_f32_e32 v97, v97, v105
	v_mul_f32_e32 v98, v98, v106
	v_mul_f32_e32 v99, v99, v107
	v_mul_f32_e32 v100, v100, v108
	v_mul_f32_e32 v101, v101, v109
	v_mul_f32_e32 v102, v102, v110
	v_mul_f32_e32 v103, v103, v111
	v_cvt_pk_bf16_f32 v96, v96, v97
	v_cvt_pk_bf16_f32 v97, v98, v99
	v_cvt_pk_bf16_f32 v98, v100, v101
	v_cvt_pk_bf16_f32 v99, v102, v103
	global_store_dwordx4 v13, v[96:99], s[82:83]
	s_mov_b32 s87, s88
	s_branch .Lp0_iloop
.Lp0_ilast0:
	s_waitcnt vmcnt(0)
	ds_write_b32 v4, v32
	ds_write_b32 v4, v33 offset:4
	ds_write_b32 v4, v34 offset:8
	ds_write_b32 v4, v35 offset:12
	ds_write_b32 v4, v36 offset:1056
	ds_write_b32 v4, v37 offset:1060
	ds_write_b32 v4, v38 offset:1064
	ds_write_b32 v4, v39 offset:1068
	ds_write_b32 v4, v40 offset:2112
	ds_write_b32 v4, v41 offset:2116
	ds_write_b32 v4, v42 offset:2120
	ds_write_b32 v4, v43 offset:2124
	ds_write_b32 v4, v44 offset:3168
	ds_write_b32 v4, v45 offset:3172
	ds_write_b32 v4, v46 offset:3176
	ds_write_b32 v4, v47 offset:3180
	ds_write_b32 v4, v48 offset:4224
	ds_write_b32 v4, v49 offset:4228
	ds_write_b32 v4, v50 offset:4232
	ds_write_b32 v4, v51 offset:4236
	ds_write_b32 v4, v52 offset:5280
	ds_write_b32 v4, v53 offset:5284
	ds_write_b32 v4, v54 offset:5288
	ds_write_b32 v4, v55 offset:5292
	ds_write_b32 v4, v56 offset:6336
	ds_write_b32 v4, v57 offset:6340
	ds_write_b32 v4, v58 offset:6344
	ds_write_b32 v4, v59 offset:6348
	ds_write_b32 v4, v60 offset:7392
	ds_write_b32 v4, v61 offset:7396
	ds_write_b32 v4, v62 offset:7400
	ds_write_b32 v4, v63 offset:7404
	s_waitcnt lgkmcnt(0)
	s_lshl_b32 s92, s28, 3
	ds_read_b32 v32, v5
	ds_read_b32 v33, v5 offset:132
	ds_read_b32 v34, v5 offset:264
	ds_read_b32 v35, v5 offset:396
	ds_read_b32 v36, v5 offset:528
	ds_read_b32 v37, v5 offset:660
	ds_read_b32 v38, v5 offset:792
	ds_read_b32 v39, v5 offset:924
	ds_read_b32 v40, v5 offset:32
	ds_read_b32 v41, v5 offset:164
	ds_read_b32 v42, v5 offset:296
	ds_read_b32 v43, v5 offset:428
	ds_read_b32 v44, v5 offset:560
	ds_read_b32 v45, v5 offset:692
	ds_read_b32 v46, v5 offset:824
	ds_read_b32 v47, v5 offset:956
	s_waitcnt lgkmcnt(8)
	v_mul_f32_e32 v32, v32, v64
	v_mul_f32_e32 v33, v33, v65
	v_mul_f32_e32 v34, v34, v66
	v_mul_f32_e32 v35, v35, v67
	v_mul_f32_e32 v36, v36, v68
	v_mul_f32_e32 v37, v37, v69
	v_mul_f32_e32 v38, v38, v70
	v_mul_f32_e32 v39, v39, v71
	v_cvt_pk_bf16_f32 v32, v32, v33
	v_cvt_pk_bf16_f32 v33, v34, v35
	v_cvt_pk_bf16_f32 v34, v36, v37
	v_cvt_pk_bf16_f32 v35, v38, v39
	global_store_dwordx4 v11, v[32:35], s[26:27]
	s_add_u32 s26, s26, s92
	s_addc_u32 s27, s27, 0
	s_waitcnt lgkmcnt(0)
	v_mul_f32_e32 v40, v40, v64
	v_mul_f32_e32 v41, v41, v65
	v_mul_f32_e32 v42, v42, v66
	v_mul_f32_e32 v43, v43, v67
	v_mul_f32_e32 v44, v44, v68
	v_mul_f32_e32 v45, v45, v69
	v_mul_f32_e32 v46, v46, v70
	v_mul_f32_e32 v47, v47, v71
	v_cvt_pk_bf16_f32 v40, v40, v41
	v_cvt_pk_bf16_f32 v41, v42, v43
	v_cvt_pk_bf16_f32 v42, v44, v45
	v_cvt_pk_bf16_f32 v43, v46, v47
	global_store_dwordx4 v11, v[40:43], s[26:27]
	s_add_u32 s26, s26, s92
	s_addc_u32 s27, s27, 0
	ds_read_b32 v48, v5 offset:64
	ds_read_b32 v49, v5 offset:196
	ds_read_b32 v50, v5 offset:328
	ds_read_b32 v51, v5 offset:460
	ds_read_b32 v52, v5 offset:592
	ds_read_b32 v53, v5 offset:724
	ds_read_b32 v54, v5 offset:856
	ds_read_b32 v55, v5 offset:988
	ds_read_b32 v56, v5 offset:96
	ds_read_b32 v57, v5 offset:228
	ds_read_b32 v58, v5 offset:360
	ds_read_b32 v59, v5 offset:492
	ds_read_b32 v60, v5 offset:624
	ds_read_b32 v61, v5 offset:756
	ds_read_b32 v62, v5 offset:888
	ds_read_b32 v63, v5 offset:1020
	s_waitcnt lgkmcnt(8)
	v_mul_f32_e32 v48, v48, v64
	v_mul_f32_e32 v49, v49, v65
	v_mul_f32_e32 v50, v50, v66
	v_mul_f32_e32 v51, v51, v67
	v_mul_f32_e32 v52, v52, v68
	v_mul_f32_e32 v53, v53, v69
	v_mul_f32_e32 v54, v54, v70
	v_mul_f32_e32 v55, v55, v71
	v_cvt_pk_bf16_f32 v48, v48, v49
	v_cvt_pk_bf16_f32 v49, v50, v51
	v_cvt_pk_bf16_f32 v50, v52, v53
	v_cvt_pk_bf16_f32 v51, v54, v55
	global_store_dwordx4 v11, v[48:51], s[26:27]
	s_add_u32 s26, s26, s92
	s_addc_u32 s27, s27, 0
	s_waitcnt lgkmcnt(0)
	v_mul_f32_e32 v56, v56, v64
	v_mul_f32_e32 v57, v57, v65
	v_mul_f32_e32 v58, v58, v66
	v_mul_f32_e32 v59, v59, v67
	v_mul_f32_e32 v60, v60, v68
	v_mul_f32_e32 v61, v61, v69
	v_mul_f32_e32 v62, v62, v70
	v_mul_f32_e32 v63, v63, v71
	v_cvt_pk_bf16_f32 v56, v56, v57
	v_cvt_pk_bf16_f32 v57, v58, v59
	v_cvt_pk_bf16_f32 v58, v60, v61
	v_cvt_pk_bf16_f32 v59, v62, v63
	global_store_dwordx4 v11, v[56:59], s[26:27]
	s_branch .Lp0_items_done
.Lp0_ilast1:
	s_waitcnt vmcnt(0)
	ds_write_b32 v4, v72
	ds_write_b32 v4, v73 offset:4
	ds_write_b32 v4, v74 offset:8
	ds_write_b32 v4, v75 offset:12
	ds_write_b32 v4, v76 offset:1056
	ds_write_b32 v4, v77 offset:1060
	ds_write_b32 v4, v78 offset:1064
	ds_write_b32 v4, v79 offset:1068
	ds_write_b32 v4, v80 offset:2112
	ds_write_b32 v4, v81 offset:2116
	ds_write_b32 v4, v82 offset:2120
	ds_write_b32 v4, v83 offset:2124
	ds_write_b32 v4, v84 offset:3168
	ds_write_b32 v4, v85 offset:3172
	ds_write_b32 v4, v86 offset:3176
	ds_write_b32 v4, v87 offset:3180
	ds_write_b32 v4, v88 offset:4224
	ds_write_b32 v4, v89 offset:4228
	ds_write_b32 v4, v90 offset:4232
	ds_write_b32 v4, v91 offset:4236
	ds_write_b32 v4, v92 offset:5280
	ds_write_b32 v4, v93 offset:5284
	ds_write_b32 v4, v94 offset:5288
	ds_write_b32 v4, v95 offset:5292
	ds_write_b32 v4, v96 offset:6336
	ds_write_b32 v4, v97 offset:6340
	ds_write_b32 v4, v98 offset:6344
	ds_write_b32 v4, v99 offset:6348
	ds_write_b32 v4, v100 offset:7392
	ds_write_b32 v4, v101 offset:7396
	ds_write_b32 v4, v102 offset:7400
	ds_write_b32 v4, v103 offset:7404
	s_waitcnt lgkmcnt(0)
	s_lshl_b32 s92, s86, 3
	ds_read_b32 v72, v5
	ds_read_b32 v73, v5 offset:132
	ds_read_b32 v74, v5 offset:264
	ds_read_b32 v75, v5 offset:396
	ds_read_b32 v76, v5 offset:528
	ds_read_b32 v77, v5 offset:660
	ds_read_b32 v78, v5 offset:792
	ds_read_b32 v79, v5 offset:924
	ds_read_b32 v80, v5 offset:32
	ds_read_b32 v81, v5 offset:164
	ds_read_b32 v82, v5 offset:296
	ds_read_b32 v83, v5 offset:428
	ds_read_b32 v84, v5 offset:560
	ds_read_b32 v85, v5 offset:692
	ds_read_b32 v86, v5 offset:824
	ds_read_b32 v87, v5 offset:956
	s_waitcnt lgkmcnt(8)
	v_mul_f32_e32 v72, v72, v104
	v_mul_f32_e32 v73, v73, v105
	v_mul_f32_e32 v74, v74, v106
	v_mul_f32_e32 v75, v75, v107
	v_mul_f32_e32 v76, v76, v108
	v_mul_f32_e32 v77, v77, v109
	v_mul_f32_e32 v78, v78, v110
	v_mul_f32_e32 v79, v79, v111
	v_cvt_pk_bf16_f32 v72, v72, v73
	v_cvt_pk_bf16_f32 v73, v74, v75
	v_cvt_pk_bf16_f32 v74, v76, v77
	v_cvt_pk_bf16_f32 v75, v78, v79
	global_store_dwordx4 v13, v[72:75], s[82:83]
	s_add_u32 s82, s82, s92
	s_addc_u32 s83, s83, 0
	s_waitcnt lgkmcnt(0)
	v_mul_f32_e32 v80, v80, v104
	v_mul_f32_e32 v81, v81, v105
	v_mul_f32_e32 v82, v82, v106
	v_mul_f32_e32 v83, v83, v107
	v_mul_f32_e32 v84, v84, v108
	v_mul_f32_e32 v85, v85, v109
	v_mul_f32_e32 v86, v86, v110
	v_mul_f32_e32 v87, v87, v111
	v_cvt_pk_bf16_f32 v80, v80, v81
	v_cvt_pk_bf16_f32 v81, v82, v83
	v_cvt_pk_bf16_f32 v82, v84, v85
	v_cvt_pk_bf16_f32 v83, v86, v87
	global_store_dwordx4 v13, v[80:83], s[82:83]
	s_add_u32 s82, s82, s92
	s_addc_u32 s83, s83, 0
	ds_read_b32 v88, v5 offset:64
	ds_read_b32 v89, v5 offset:196
	ds_read_b32 v90, v5 offset:328
	ds_read_b32 v91, v5 offset:460
	ds_read_b32 v92, v5 offset:592
	ds_read_b32 v93, v5 offset:724
	ds_read_b32 v94, v5 offset:856
	ds_read_b32 v95, v5 offset:988
	ds_read_b32 v96, v5 offset:96
	ds_read_b32 v97, v5 offset:228
	ds_read_b32 v98, v5 offset:360
	ds_read_b32 v99, v5 offset:492
	ds_read_b32 v100, v5 offset:624
	ds_read_b32 v101, v5 offset:756
	ds_read_b32 v102, v5 offset:888
	ds_read_b32 v103, v5 offset:1020
	s_waitcnt lgkmcnt(8)
	v_mul_f32_e32 v88, v88, v104
	v_mul_f32_e32 v89, v89, v105
	v_mul_f32_e32 v90, v90, v106
	v_mul_f32_e32 v91, v91, v107
	v_mul_f32_e32 v92, v92, v108
	v_mul_f32_e32 v93, v93, v109
	v_mul_f32_e32 v94, v94, v110
	v_mul_f32_e32 v95, v95, v111
	v_cvt_pk_bf16_f32 v88, v88, v89
	v_cvt_pk_bf16_f32 v89, v90, v91
	v_cvt_pk_bf16_f32 v90, v92, v93
	v_cvt_pk_bf16_f32 v91, v94, v95
	global_store_dwordx4 v13, v[88:91], s[82:83]
	s_add_u32 s82, s82, s92
	s_addc_u32 s83, s83, 0
	s_waitcnt lgkmcnt(0)
	v_mul_f32_e32 v96, v96, v104
	v_mul_f32_e32 v97, v97, v105
	v_mul_f32_e32 v98, v98, v106
	v_mul_f32_e32 v99, v99, v107
	v_mul_f32_e32 v100, v100, v108
	v_mul_f32_e32 v101, v101, v109
	v_mul_f32_e32 v102, v102, v110
	v_mul_f32_e32 v103, v103, v111
	v_cvt_pk_bf16_f32 v96, v96, v97
	v_cvt_pk_bf16_f32 v97, v98, v99
	v_cvt_pk_bf16_f32 v98, v100, v101
	v_cvt_pk_bf16_f32 v99, v102, v103
	global_store_dwordx4 v13, v[96:99], s[82:83]
.Lp0_items_done:
	s_load_dwordx4 s[48:51], s[0:1], 0x0
	s_load_dwordx2 s[52:53], s[0:1], 0x40
	s_load_dwordx4 s[56:59], s[0:1], 0x30
	v_and_b32_e32 v1, 63, v206
	v_lshlrev_b32_e32 v2, 4, v1
	v_lshlrev_b32_e32 v3, 3, v1
	v_xor_b32_e32 v4, 1, v1
	v_lshlrev_b32_e32 v4, 2, v4
	v_xor_b32_e32 v5, 2, v1
	v_lshlrev_b32_e32 v5, 2, v5
	v_xor_b32_e32 v6, 4, v1
	v_lshlrev_b32_e32 v6, 2, v6
	v_xor_b32_e32 v7, 8, v1
	v_lshlrev_b32_e32 v7, 2, v7
	v_xor_b32_e32 v8, 16, v1
	v_lshlrev_b32_e32 v8, 2, v8
	v_xor_b32_e32 v9, 32, v1
	v_lshlrev_b32_e32 v9, 2, v9
	v_mov_b32_e32 v12, 0
	v_lshlrev_b32_e32 v13, 2, v1
	s_waitcnt lgkmcnt(0)
	s_add_u32 s87, s33, s3
	s_cmp_ge_u32 s87, 0x10100
	s_cbranch_scc1 .Lp0_tok_done
	s_cmp_lt_u32 s87, 0x10000
	s_cselect_b32 s20, s48, s50
	s_cselect_b32 s21, s49, s51
	s_cselect_b32 s92, 0, 0x10000
	s_sub_u32 s92, s87, s92
	s_lshl_b32 s92, s92, 12
	s_add_u32 s20, s20, s92
	s_addc_u32 s21, s21, 0
	s_mov_b32 s24, s87
	global_load_dwordx4 v[16:19], v2, s[20:21]
	global_load_dwordx4 v[20:23], v2, s[20:21] offset:1024
	global_load_dwordx4 v[24:27], v2, s[20:21] offset:2048
	global_load_dwordx4 v[28:31], v2, s[20:21] offset:3072
.Lp0_tok_loop:
	s_add_u32 s88, s87, s34
	s_cmp_ge_u32 s88, 0x10100
	s_cbranch_scc1 .Lp0_tok_last0
	s_cmp_lt_u32 s88, 0x10000
	s_cselect_b32 s22, s48, s50
	s_cselect_b32 s23, s49, s51
	s_cselect_b32 s92, 0, 0x10000
	s_sub_u32 s92, s88, s92
	s_lshl_b32 s92, s92, 12
	s_add_u32 s22, s22, s92
	s_addc_u32 s23, s23, 0
	s_mov_b32 s25, s88
	global_load_dwordx4 v[32:35], v2, s[22:23]
	global_load_dwordx4 v[36:39], v2, s[22:23] offset:1024
	global_load_dwordx4 v[40:43], v2, s[22:23] offset:2048
	global_load_dwordx4 v[44:47], v2, s[22:23] offset:3072
	s_waitcnt vmcnt(4)
	v_mul_f32_e32 v10, v16, v16
	v_fmac_f32_e32 v10, v17, v17
	v_fmac_f32_e32 v10, v18, v18
	v_fmac_f32_e32 v10, v19, v19
	v_fmac_f32_e32 v10, v20, v20
	v_fmac_f32_e32 v10, v21, v21
	v_fmac_f32_e32 v10, v22, v22
	v_fmac_f32_e32 v10, v23, v23
	v_fmac_f32_e32 v10, v24, v24
	v_fmac_f32_e32 v10, v25, v25
	v_fmac_f32_e32 v10, v26, v26
	v_fmac_f32_e32 v10, v27, v27
	v_fmac_f32_e32 v10, v28, v28
	v_fmac_f32_e32 v10, v29, v29
	v_fmac_f32_e32 v10, v30, v30
	v_fmac_f32_e32 v10, v31, v31
	s_nop 0
	ds_bpermute_b32 v11, v4, v10
	s_waitcnt lgkmcnt(0)
	v_add_f32_e32 v10, v10, v11
	s_nop 0
	ds_bpermute_b32 v11, v5, v10
	s_waitcnt lgkmcnt(0)
	v_add_f32_e32 v10, v10, v11
	s_nop 0
	ds_bpermute_b32 v11, v6, v10
	s_waitcnt lgkmcnt(0)
	v_add_f32_e32 v10, v10, v11
	s_nop 0
	ds_bpermute_b32 v11, v7, v10
	s_waitcnt lgkmcnt(0)
	v_add_f32_e32 v10, v10, v11
	s_nop 0
	ds_bpermute_b32 v11, v8, v10
	s_waitcnt lgkmcnt(0)
	v_add_f32_e32 v10, v10, v11
	s_nop 0
	ds_bpermute_b32 v11, v9, v10
	s_waitcnt lgkmcnt(0)
	v_add_f32_e32 v10, v10, v11
	s_nop 0
	s_lshl_b32 s92, s24, 11
	s_add_u32 s26, s38, s92
	s_addc_u32 s27, s39, 0
	s_add_u32 s26, s26, 0x9e00000
	s_addc_u32 s27, s27, 0
	v_cvt_pk_bf16_f32 v16, v16, v17
	v_cvt_pk_bf16_f32 v17, v18, v19
	global_store_dwordx2 v3, v[16:17], s[26:27]
	v_cvt_pk_bf16_f32 v20, v20, v21
	v_cvt_pk_bf16_f32 v21, v22, v23
	global_store_dwordx2 v3, v[20:21], s[26:27] offset:512
	v_cvt_pk_bf16_f32 v24, v24, v25
	v_cvt_pk_bf16_f32 v25, v26, v27
	global_store_dwordx2 v3, v[24:25], s[26:27] offset:1024
	v_cvt_pk_bf16_f32 v28, v28, v29
	v_cvt_pk_bf16_f32 v29, v30, v31
	global_store_dwordx2 v3, v[28:29], s[26:27] offset:1536
	s_lshl_b32 s92, s24, 6
	s_add_u32 s26, s38, s92
	s_addc_u32 s27, s39, 0
	s_add_u32 s26, s26, 0x4100000
	s_addc_u32 s27, s27, 0
	v_cmp_eq_u32_e32 vcc, 0, v1
	s_nop 1
	v_cndmask_b32_e32 v11, v12, v10, vcc
	v_cmp_gt_u32_e32 vcc, 16, v1
	s_and_saveexec_b64 s[28:29], vcc
	global_store_dword v13, v11, s[26:27]
	s_mov_b64 exec, s[28:29]
	s_mov_b32 s87, s88
	s_add_u32 s88, s87, s34
	s_cmp_ge_u32 s88, 0x10100
	s_cbranch_scc1 .Lp0_tok_last1
	s_cmp_lt_u32 s88, 0x10000
	s_cselect_b32 s20, s48, s50
	s_cselect_b32 s21, s49, s51
	s_cselect_b32 s92, 0, 0x10000
	s_sub_u32 s92, s88, s92
	s_lshl_b32 s92, s92, 12
	s_add_u32 s20, s20, s92
	s_addc_u32 s21, s21, 0
	s_mov_b32 s24, s88
	global_load_dwordx4 v[16:19], v2, s[20:21]
	global_load_dwordx4 v[20:23], v2, s[20:21] offset:1024
	global_load_dwordx4 v[24:27], v2, s[20:21] offset:2048
	global_load_dwordx4 v[28:31], v2, s[20:21] offset:3072
	s_waitcnt vmcnt(4)
	v_mul_f32_e32 v10, v32, v32
	v_fmac_f32_e32 v10, v33, v33
	v_fmac_f32_e32 v10, v34, v34
	v_fmac_f32_e32 v10, v35, v35
	v_fmac_f32_e32 v10, v36, v36
	v_fmac_f32_e32 v10, v37, v37
	v_fmac_f32_e32 v10, v38, v38
	v_fmac_f32_e32 v10, v39, v39
	v_fmac_f32_e32 v10, v40, v40
	v_fmac_f32_e32 v10, v41, v41
	v_fmac_f32_e32 v10, v42, v42
	v_fmac_f32_e32 v10, v43, v43
	v_fmac_f32_e32 v10, v44, v44
	v_fmac_f32_e32 v10, v45, v45
	v_fmac_f32_e32 v10, v46, v46
	v_fmac_f32_e32 v10, v47, v47
	s_nop 0
	ds_bpermute_b32 v11, v4, v10
	s_waitcnt lgkmcnt(0)
	v_add_f32_e32 v10, v10, v11
	s_nop 0
	ds_bpermute_b32 v11, v5, v10
	s_waitcnt lgkmcnt(0)
	v_add_f32_e32 v10, v10, v11
	s_nop 0
	ds_bpermute_b32 v11, v6, v10
	s_waitcnt lgkmcnt(0)
	v_add_f32_e32 v10, v10, v11
	s_nop 0
	ds_bpermute_b32 v11, v7, v10
	s_waitcnt lgkmcnt(0)
	v_add_f32_e32 v10, v10, v11
	s_nop 0
	ds_bpermute_b32 v11, v8, v10
	s_waitcnt lgkmcnt(0)
	v_add_f32_e32 v10, v10, v11
	s_nop 0
	ds_bpermute_b32 v11, v9, v10
	s_waitcnt lgkmcnt(0)
	v_add_f32_e32 v10, v10, v11
	s_nop 0
	s_lshl_b32 s92, s25, 11
	s_add_u32 s26, s38, s92
	s_addc_u32 s27, s39, 0
	s_add_u32 s26, s26, 0x9e00000
	s_addc_u32 s27, s27, 0
	v_cvt_pk_bf16_f32 v32, v32, v33
	v_cvt_pk_bf16_f32 v33, v34, v35
	global_store_dwordx2 v3, v[32:33], s[26:27]
	v_cvt_pk_bf16_f32 v36, v36, v37
	v_cvt_pk_bf16_f32 v37, v38, v39
	global_store_dwordx2 v3, v[36:37], s[26:27] offset:512
	v_cvt_pk_bf16_f32 v40, v40, v41
	v_cvt_pk_bf16_f32 v41, v42, v43
	global_store_dwordx2 v3, v[40:41], s[26:27] offset:1024
	v_cvt_pk_bf16_f32 v44, v44, v45
	v_cvt_pk_bf16_f32 v45, v46, v47
	global_store_dwordx2 v3, v[44:45], s[26:27] offset:1536
	s_lshl_b32 s92, s25, 6
	s_add_u32 s26, s38, s92
	s_addc_u32 s27, s39, 0
	s_add_u32 s26, s26, 0x4100000
	s_addc_u32 s27, s27, 0
	v_cmp_eq_u32_e32 vcc, 0, v1
	s_nop 1
	v_cndmask_b32_e32 v11, v12, v10, vcc
	v_cmp_gt_u32_e32 vcc, 16, v1
	s_and_saveexec_b64 s[28:29], vcc
	global_store_dword v13, v11, s[26:27]
	s_mov_b64 exec, s[28:29]
	s_mov_b32 s87, s88
	s_branch .Lp0_tok_loop
.Lp0_tok_last0:
	s_waitcnt vmcnt(0)
	v_mul_f32_e32 v10, v16, v16
	v_fmac_f32_e32 v10, v17, v17
	v_fmac_f32_e32 v10, v18, v18
	v_fmac_f32_e32 v10, v19, v19
	v_fmac_f32_e32 v10, v20, v20
	v_fmac_f32_e32 v10, v21, v21
	v_fmac_f32_e32 v10, v22, v22
	v_fmac_f32_e32 v10, v23, v23
	v_fmac_f32_e32 v10, v24, v24
	v_fmac_f32_e32 v10, v25, v25
	v_fmac_f32_e32 v10, v26, v26
	v_fmac_f32_e32 v10, v27, v27
	v_fmac_f32_e32 v10, v28, v28
	v_fmac_f32_e32 v10, v29, v29
	v_fmac_f32_e32 v10, v30, v30
	v_fmac_f32_e32 v10, v31, v31
	s_nop 0
	ds_bpermute_b32 v11, v4, v10
	s_waitcnt lgkmcnt(0)
	v_add_f32_e32 v10, v10, v11
	s_nop 0
	ds_bpermute_b32 v11, v5, v10
	s_waitcnt lgkmcnt(0)
	v_add_f32_e32 v10, v10, v11
	s_nop 0
	ds_bpermute_b32 v11, v6, v10
	s_waitcnt lgkmcnt(0)
	v_add_f32_e32 v10, v10, v11
	s_nop 0
	ds_bpermute_b32 v11, v7, v10
	s_waitcnt lgkmcnt(0)
	v_add_f32_e32 v10, v10, v11
	s_nop 0
	ds_bpermute_b32 v11, v8, v10
	s_waitcnt lgkmcnt(0)
	v_add_f32_e32 v10, v10, v11
	s_nop 0
	ds_bpermute_b32 v11, v9, v10
	s_waitcnt lgkmcnt(0)
	v_add_f32_e32 v10, v10, v11
	s_nop 0
	s_lshl_b32 s92, s24, 11
	s_add_u32 s26, s38, s92
	s_addc_u32 s27, s39, 0
	s_add_u32 s26, s26, 0x9e00000
	s_addc_u32 s27, s27, 0
	v_cvt_pk_bf16_f32 v16, v16, v17
	v_cvt_pk_bf16_f32 v17, v18, v19
	global_store_dwordx2 v3, v[16:17], s[26:27]
	v_cvt_pk_bf16_f32 v20, v20, v21
	v_cvt_pk_bf16_f32 v21, v22, v23
	global_store_dwordx2 v3, v[20:21], s[26:27] offset:512
	v_cvt_pk_bf16_f32 v24, v24, v25
	v_cvt_pk_bf16_f32 v25, v26, v27
	global_store_dwordx2 v3, v[24:25], s[26:27] offset:1024
	v_cvt_pk_bf16_f32 v28, v28, v29
	v_cvt_pk_bf16_f32 v29, v30, v31
	global_store_dwordx2 v3, v[28:29], s[26:27] offset:1536
	s_lshl_b32 s92, s24, 6
	s_add_u32 s26, s38, s92
	s_addc_u32 s27, s39, 0
	s_add_u32 s26, s26, 0x4100000
	s_addc_u32 s27, s27, 0
	v_cmp_eq_u32_e32 vcc, 0, v1
	s_nop 1
	v_cndmask_b32_e32 v11, v12, v10, vcc
	v_cmp_gt_u32_e32 vcc, 16, v1
	s_and_saveexec_b64 s[28:29], vcc
	global_store_dword v13, v11, s[26:27]
	s_mov_b64 exec, s[28:29]
	s_branch .Lp0_tok_done
.Lp0_tok_last1:
	s_waitcnt vmcnt(0)
	v_mul_f32_e32 v10, v32, v32
	v_fmac_f32_e32 v10, v33, v33
	v_fmac_f32_e32 v10, v34, v34
	v_fmac_f32_e32 v10, v35, v35
	v_fmac_f32_e32 v10, v36, v36
	v_fmac_f32_e32 v10, v37, v37
	v_fmac_f32_e32 v10, v38, v38
	v_fmac_f32_e32 v10, v39, v39
	v_fmac_f32_e32 v10, v40, v40
	v_fmac_f32_e32 v10, v41, v41
	v_fmac_f32_e32 v10, v42, v42
	v_fmac_f32_e32 v10, v43, v43
	v_fmac_f32_e32 v10, v44, v44
	v_fmac_f32_e32 v10, v45, v45
	v_fmac_f32_e32 v10, v46, v46
	v_fmac_f32_e32 v10, v47, v47
	s_nop 0
	ds_bpermute_b32 v11, v4, v10
	s_waitcnt lgkmcnt(0)
	v_add_f32_e32 v10, v10, v11
	s_nop 0
	ds_bpermute_b32 v11, v5, v10
	s_waitcnt lgkmcnt(0)
	v_add_f32_e32 v10, v10, v11
	s_nop 0
	ds_bpermute_b32 v11, v6, v10
	s_waitcnt lgkmcnt(0)
	v_add_f32_e32 v10, v10, v11
	s_nop 0
	ds_bpermute_b32 v11, v7, v10
	s_waitcnt lgkmcnt(0)
	v_add_f32_e32 v10, v10, v11
	s_nop 0
	ds_bpermute_b32 v11, v8, v10
	s_waitcnt lgkmcnt(0)
	v_add_f32_e32 v10, v10, v11
	s_nop 0
	ds_bpermute_b32 v11, v9, v10
	s_waitcnt lgkmcnt(0)
	v_add_f32_e32 v10, v10, v11
	s_nop 0
	s_lshl_b32 s92, s25, 11
	s_add_u32 s26, s38, s92
	s_addc_u32 s27, s39, 0
	s_add_u32 s26, s26, 0x9e00000
	s_addc_u32 s27, s27, 0
	v_cvt_pk_bf16_f32 v32, v32, v33
	v_cvt_pk_bf16_f32 v33, v34, v35
	global_store_dwordx2 v3, v[32:33], s[26:27]
	v_cvt_pk_bf16_f32 v36, v36, v37
	v_cvt_pk_bf16_f32 v37, v38, v39
	global_store_dwordx2 v3, v[36:37], s[26:27] offset:512
	v_cvt_pk_bf16_f32 v40, v40, v41
	v_cvt_pk_bf16_f32 v41, v42, v43
	global_store_dwordx2 v3, v[40:41], s[26:27] offset:1024
	v_cvt_pk_bf16_f32 v44, v44, v45
	v_cvt_pk_bf16_f32 v45, v46, v47
	global_store_dwordx2 v3, v[44:45], s[26:27] offset:1536
	s_lshl_b32 s92, s25, 6
	s_add_u32 s26, s38, s92
	s_addc_u32 s27, s39, 0
	s_add_u32 s26, s26, 0x4100000
	s_addc_u32 s27, s27, 0
	v_cmp_eq_u32_e32 vcc, 0, v1
	s_nop 1
	v_cndmask_b32_e32 v11, v12, v10, vcc
	v_cmp_gt_u32_e32 vcc, 16, v1
	s_and_saveexec_b64 s[28:29], vcc
	global_store_dword v13, v11, s[26:27]
	s_mov_b64 exec, s[28:29]
.Lp0_tok_done:
	s_add_u32 s87, s33, s3
	s_cmp_ge_u32 s87, 0x2000
	s_cbranch_scc1 .Lp0_mem_done
	s_mov_b32 s20, s52
	s_mov_b32 s21, s53
	s_lshl_b32 s92, s87, 12
	s_add_u32 s20, s20, s92
	s_addc_u32 s21, s21, 0
	s_mov_b32 s24, s87
	global_load_dwordx4 v[16:19], v2, s[20:21]
	global_load_dwordx4 v[20:23], v2, s[20:21] offset:1024
	global_load_dwordx4 v[24:27], v2, s[20:21] offset:2048
	global_load_dwordx4 v[28:31], v2, s[20:21] offset:3072
.Lp0_mem_loop:
	s_add_u32 s88, s87, s34
	s_cmp_ge_u32 s88, 0x2000
	s_cbranch_scc1 .Lp0_mem_last0
	s_mov_b32 s22, s52
	s_mov_b32 s23, s53
	s_lshl_b32 s92, s88, 12
	s_add_u32 s22, s22, s92
	s_addc_u32 s23, s23, 0
	s_mov_b32 s25, s88
	global_load_dwordx4 v[32:35], v2, s[22:23]
	global_load_dwordx4 v[36:39], v2, s[22:23] offset:1024
	global_load_dwordx4 v[40:43], v2, s[22:23] offset:2048
	global_load_dwordx4 v[44:47], v2, s[22:23] offset:3072
	s_waitcnt vmcnt(4)
	v_mul_f32_e32 v10, v16, v16
	v_fmac_f32_e32 v10, v17, v17
	v_fmac_f32_e32 v10, v18, v18
	v_fmac_f32_e32 v10, v19, v19
	v_fmac_f32_e32 v10, v20, v20
	v_fmac_f32_e32 v10, v21, v21
	v_fmac_f32_e32 v10, v22, v22
	v_fmac_f32_e32 v10, v23, v23
	v_fmac_f32_e32 v10, v24, v24
	v_fmac_f32_e32 v10, v25, v25
	v_fmac_f32_e32 v10, v26, v26
	v_fmac_f32_e32 v10, v27, v27
	v_fmac_f32_e32 v10, v28, v28
	v_fmac_f32_e32 v10, v29, v29
	v_fmac_f32_e32 v10, v30, v30
	v_fmac_f32_e32 v10, v31, v31
	s_nop 0
	ds_bpermute_b32 v11, v4, v10
	s_waitcnt lgkmcnt(0)
	v_add_f32_e32 v10, v10, v11
	s_nop 0
	ds_bpermute_b32 v11, v5, v10
	s_waitcnt lgkmcnt(0)
	v_add_f32_e32 v10, v10, v11
	s_nop 0
	ds_bpermute_b32 v11, v6, v10
	s_waitcnt lgkmcnt(0)
	v_add_f32_e32 v10, v10, v11
	s_nop 0
	ds_bpermute_b32 v11, v7, v10
	s_waitcnt lgkmcnt(0)
	v_add_f32_e32 v10, v10, v11
	s_nop 0
	ds_bpermute_b32 v11, v8, v10
	s_waitcnt lgkmcnt(0)
	v_add_f32_e32 v10, v10, v11
	s_nop 0
	ds_bpermute_b32 v11, v9, v10
	s_waitcnt lgkmcnt(0)
	v_add_f32_e32 v10, v10, v11
	s_nop 0
	s_lshl_b32 s92, s24, 11
	s_add_u32 s26, s38, s92
	s_addc_u32 s27, s39, 0
	s_add_u32 s26, s26, 0x5e00000
	s_addc_u32 s27, s27, 0
	v_cvt_pk_bf16_f32 v16, v16, v17
	v_cvt_pk_bf16_f32 v17, v18, v19
	global_store_dwordx2 v3, v[16:17], s[26:27]
	v_cvt_pk_bf16_f32 v20, v20, v21
	v_cvt_pk_bf16_f32 v21, v22, v23
	global_store_dwordx2 v3, v[20:21], s[26:27] offset:512
	v_cvt_pk_bf16_f32 v24, v24, v25
	v_cvt_pk_bf16_f32 v25, v26, v27
	global_store_dwordx2 v3, v[24:25], s[26:27] offset:1024
	v_cvt_pk_bf16_f32 v28, v28, v29
	v_cvt_pk_bf16_f32 v29, v30, v31
	global_store_dwordx2 v3, v[28:29], s[26:27] offset:1536
	s_lshl_b32 s92, s24, 2
	s_add_u32 s26, s38, s92
	s_addc_u32 s27, s39, 0
	s_add_u32 s26, s26, 0x5a00000
	s_addc_u32 s27, s27, 0
	v_cmp_eq_u32_e32 vcc, 0, v1
	s_and_saveexec_b64 s[28:29], vcc
	global_store_dword v12, v10, s[26:27]
	s_mov_b64 exec, s[28:29]
	s_mov_b32 s87, s88
	s_add_u32 s88, s87, s34
	s_cmp_ge_u32 s88, 0x2000
	s_cbranch_scc1 .Lp0_mem_last1
	s_mov_b32 s20, s52
	s_mov_b32 s21, s53
	s_lshl_b32 s92, s88, 12
	s_add_u32 s20, s20, s92
	s_addc_u32 s21, s21, 0
	s_mov_b32 s24, s88
	global_load_dwordx4 v[16:19], v2, s[20:21]
	global_load_dwordx4 v[20:23], v2, s[20:21] offset:1024
	global_load_dwordx4 v[24:27], v2, s[20:21] offset:2048
	global_load_dwordx4 v[28:31], v2, s[20:21] offset:3072
	s_waitcnt vmcnt(4)
	v_mul_f32_e32 v10, v32, v32
	v_fmac_f32_e32 v10, v33, v33
	v_fmac_f32_e32 v10, v34, v34
	v_fmac_f32_e32 v10, v35, v35
	v_fmac_f32_e32 v10, v36, v36
	v_fmac_f32_e32 v10, v37, v37
	v_fmac_f32_e32 v10, v38, v38
	v_fmac_f32_e32 v10, v39, v39
	v_fmac_f32_e32 v10, v40, v40
	v_fmac_f32_e32 v10, v41, v41
	v_fmac_f32_e32 v10, v42, v42
	v_fmac_f32_e32 v10, v43, v43
	v_fmac_f32_e32 v10, v44, v44
	v_fmac_f32_e32 v10, v45, v45
	v_fmac_f32_e32 v10, v46, v46
	v_fmac_f32_e32 v10, v47, v47
	s_nop 0
	ds_bpermute_b32 v11, v4, v10
	s_waitcnt lgkmcnt(0)
	v_add_f32_e32 v10, v10, v11
	s_nop 0
	ds_bpermute_b32 v11, v5, v10
	s_waitcnt lgkmcnt(0)
	v_add_f32_e32 v10, v10, v11
	s_nop 0
	ds_bpermute_b32 v11, v6, v10
	s_waitcnt lgkmcnt(0)
	v_add_f32_e32 v10, v10, v11
	s_nop 0
	ds_bpermute_b32 v11, v7, v10
	s_waitcnt lgkmcnt(0)
	v_add_f32_e32 v10, v10, v11
	s_nop 0
	ds_bpermute_b32 v11, v8, v10
	s_waitcnt lgkmcnt(0)
	v_add_f32_e32 v10, v10, v11
	s_nop 0
	ds_bpermute_b32 v11, v9, v10
	s_waitcnt lgkmcnt(0)
	v_add_f32_e32 v10, v10, v11
	s_nop 0
	s_lshl_b32 s92, s25, 11
	s_add_u32 s26, s38, s92
	s_addc_u32 s27, s39, 0
	s_add_u32 s26, s26, 0x5e00000
	s_addc_u32 s27, s27, 0
	v_cvt_pk_bf16_f32 v32, v32, v33
	v_cvt_pk_bf16_f32 v33, v34, v35
	global_store_dwordx2 v3, v[32:33], s[26:27]
	v_cvt_pk_bf16_f32 v36, v36, v37
	v_cvt_pk_bf16_f32 v37, v38, v39
	global_store_dwordx2 v3, v[36:37], s[26:27] offset:512
	v_cvt_pk_bf16_f32 v40, v40, v41
	v_cvt_pk_bf16_f32 v41, v42, v43
	global_store_dwordx2 v3, v[40:41], s[26:27] offset:1024
	v_cvt_pk_bf16_f32 v44, v44, v45
	v_cvt_pk_bf16_f32 v45, v46, v47
	global_store_dwordx2 v3, v[44:45], s[26:27] offset:1536
	s_lshl_b32 s92, s25, 2
	s_add_u32 s26, s38, s92
	s_addc_u32 s27, s39, 0
	s_add_u32 s26, s26, 0x5a00000
	s_addc_u32 s27, s27, 0
	v_cmp_eq_u32_e32 vcc, 0, v1
	s_and_saveexec_b64 s[28:29], vcc
	global_store_dword v12, v10, s[26:27]
	s_mov_b64 exec, s[28:29]
	s_mov_b32 s87, s88
	s_branch .Lp0_mem_loop
.Lp0_mem_last0:
	s_waitcnt vmcnt(0)
	v_mul_f32_e32 v10, v16, v16
	v_fmac_f32_e32 v10, v17, v17
	v_fmac_f32_e32 v10, v18, v18
	v_fmac_f32_e32 v10, v19, v19
	v_fmac_f32_e32 v10, v20, v20
	v_fmac_f32_e32 v10, v21, v21
	v_fmac_f32_e32 v10, v22, v22
	v_fmac_f32_e32 v10, v23, v23
	v_fmac_f32_e32 v10, v24, v24
	v_fmac_f32_e32 v10, v25, v25
	v_fmac_f32_e32 v10, v26, v26
	v_fmac_f32_e32 v10, v27, v27
	v_fmac_f32_e32 v10, v28, v28
	v_fmac_f32_e32 v10, v29, v29
	v_fmac_f32_e32 v10, v30, v30
	v_fmac_f32_e32 v10, v31, v31
	s_nop 0
	ds_bpermute_b32 v11, v4, v10
	s_waitcnt lgkmcnt(0)
	v_add_f32_e32 v10, v10, v11
	s_nop 0
	ds_bpermute_b32 v11, v5, v10
	s_waitcnt lgkmcnt(0)
	v_add_f32_e32 v10, v10, v11
	s_nop 0
	ds_bpermute_b32 v11, v6, v10
	s_waitcnt lgkmcnt(0)
	v_add_f32_e32 v10, v10, v11
	s_nop 0
	ds_bpermute_b32 v11, v7, v10
	s_waitcnt lgkmcnt(0)
	v_add_f32_e32 v10, v10, v11
	s_nop 0
	ds_bpermute_b32 v11, v8, v10
	s_waitcnt lgkmcnt(0)
	v_add_f32_e32 v10, v10, v11
	s_nop 0
	ds_bpermute_b32 v11, v9, v10
	s_waitcnt lgkmcnt(0)
	v_add_f32_e32 v10, v10, v11
	s_nop 0
	s_lshl_b32 s92, s24, 11
	s_add_u32 s26, s38, s92
	s_addc_u32 s27, s39, 0
	s_add_u32 s26, s26, 0x5e00000
	s_addc_u32 s27, s27, 0
	v_cvt_pk_bf16_f32 v16, v16, v17
	v_cvt_pk_bf16_f32 v17, v18, v19
	global_store_dwordx2 v3, v[16:17], s[26:27]
	v_cvt_pk_bf16_f32 v20, v20, v21
	v_cvt_pk_bf16_f32 v21, v22, v23
	global_store_dwordx2 v3, v[20:21], s[26:27] offset:512
	v_cvt_pk_bf16_f32 v24, v24, v25
	v_cvt_pk_bf16_f32 v25, v26, v27
	global_store_dwordx2 v3, v[24:25], s[26:27] offset:1024
	v_cvt_pk_bf16_f32 v28, v28, v29
	v_cvt_pk_bf16_f32 v29, v30, v31
	global_store_dwordx2 v3, v[28:29], s[26:27] offset:1536
	s_lshl_b32 s92, s24, 2
	s_add_u32 s26, s38, s92
	s_addc_u32 s27, s39, 0
	s_add_u32 s26, s26, 0x5a00000
	s_addc_u32 s27, s27, 0
	v_cmp_eq_u32_e32 vcc, 0, v1
	s_and_saveexec_b64 s[28:29], vcc
	global_store_dword v12, v10, s[26:27]
	s_mov_b64 exec, s[28:29]
	s_branch .Lp0_mem_done
.Lp0_mem_last1:
	s_waitcnt vmcnt(0)
	v_mul_f32_e32 v10, v32, v32
	v_fmac_f32_e32 v10, v33, v33
	v_fmac_f32_e32 v10, v34, v34
	v_fmac_f32_e32 v10, v35, v35
	v_fmac_f32_e32 v10, v36, v36
	v_fmac_f32_e32 v10, v37, v37
	v_fmac_f32_e32 v10, v38, v38
	v_fmac_f32_e32 v10, v39, v39
	v_fmac_f32_e32 v10, v40, v40
	v_fmac_f32_e32 v10, v41, v41
	v_fmac_f32_e32 v10, v42, v42
	v_fmac_f32_e32 v10, v43, v43
	v_fmac_f32_e32 v10, v44, v44
	v_fmac_f32_e32 v10, v45, v45
	v_fmac_f32_e32 v10, v46, v46
	v_fmac_f32_e32 v10, v47, v47
	s_nop 0
	ds_bpermute_b32 v11, v4, v10
	s_waitcnt lgkmcnt(0)
	v_add_f32_e32 v10, v10, v11
	s_nop 0
	ds_bpermute_b32 v11, v5, v10
	s_waitcnt lgkmcnt(0)
	v_add_f32_e32 v10, v10, v11
	s_nop 0
	ds_bpermute_b32 v11, v6, v10
	s_waitcnt lgkmcnt(0)
	v_add_f32_e32 v10, v10, v11
	s_nop 0
	ds_bpermute_b32 v11, v7, v10
	s_waitcnt lgkmcnt(0)
	v_add_f32_e32 v10, v10, v11
	s_nop 0
	ds_bpermute_b32 v11, v8, v10
	s_waitcnt lgkmcnt(0)
	v_add_f32_e32 v10, v10, v11
	s_nop 0
	ds_bpermute_b32 v11, v9, v10
	s_waitcnt lgkmcnt(0)
	v_add_f32_e32 v10, v10, v11
	s_nop 0
	s_lshl_b32 s92, s25, 11
	s_add_u32 s26, s38, s92
	s_addc_u32 s27, s39, 0
	s_add_u32 s26, s26, 0x5e00000
	s_addc_u32 s27, s27, 0
	v_cvt_pk_bf16_f32 v32, v32, v33
	v_cvt_pk_bf16_f32 v33, v34, v35
	global_store_dwordx2 v3, v[32:33], s[26:27]
	v_cvt_pk_bf16_f32 v36, v36, v37
	v_cvt_pk_bf16_f32 v37, v38, v39
	global_store_dwordx2 v3, v[36:37], s[26:27] offset:512
	v_cvt_pk_bf16_f32 v40, v40, v41
	v_cvt_pk_bf16_f32 v41, v42, v43
	global_store_dwordx2 v3, v[40:41], s[26:27] offset:1024
	v_cvt_pk_bf16_f32 v44, v44, v45
	v_cvt_pk_bf16_f32 v45, v46, v47
	global_store_dwordx2 v3, v[44:45], s[26:27] offset:1536
	s_lshl_b32 s92, s25, 2
	s_add_u32 s26, s38, s92
	s_addc_u32 s27, s39, 0
	s_add_u32 s26, s26, 0x5a00000
	s_addc_u32 s27, s27, 0
	v_cmp_eq_u32_e32 vcc, 0, v1
	s_and_saveexec_b64 s[28:29], vcc
	global_store_dword v12, v10, s[26:27]
	s_mov_b64 exec, s[28:29]
.Lp0_mem_done:
	s_add_u32 s87, s33, s3
	s_cmp_ge_u32 s87, 0x2000
	s_cbranch_scc1 .Lp0_cache_done
	s_cmp_lt_u32 s87, 0x1000
	s_cselect_b32 s20, s56, s58
	s_cselect_b32 s21, s57, s59
	s_and_b32 s92, s87, 0xfff
	s_lshl_b32 s92, s92, 12
	s_add_u32 s20, s20, s92
	s_addc_u32 s21, s21, 0
	s_mov_b32 s24, s87
	global_load_dwordx4 v[16:19], v2, s[20:21]
	global_load_dwordx4 v[20:23], v2, s[20:21] offset:1024
	global_load_dwordx4 v[24:27], v2, s[20:21] offset:2048
	global_load_dwordx4 v[28:31], v2, s[20:21] offset:3072
.Lp0_cache_loop:
	s_add_u32 s88, s87, s34
	s_cmp_ge_u32 s88, 0x2000
	s_cbranch_scc1 .Lp0_cache_last0
	s_cmp_lt_u32 s88, 0x1000
	s_cselect_b32 s22, s56, s58
	s_cselect_b32 s23, s57, s59
	s_and_b32 s92, s88, 0xfff
	s_lshl_b32 s92, s92, 12
	s_add_u32 s22, s22, s92
	s_addc_u32 s23, s23, 0
	s_mov_b32 s25, s88
	global_load_dwordx4 v[32:35], v2, s[22:23]
	global_load_dwordx4 v[36:39], v2, s[22:23] offset:1024
	global_load_dwordx4 v[40:43], v2, s[22:23] offset:2048
	global_load_dwordx4 v[44:47], v2, s[22:23] offset:3072
	s_waitcnt vmcnt(4)
	s_and_b32 s92, s24, 0xfff
	s_add_u32 s92, s92, 0x2000
	s_lshl_b32 s92, s92, 11
	s_add_u32 s26, s38, s92
	s_addc_u32 s27, s39, 0
	s_cmp_lt_u32 s24, 0x1000
	s_mov_b32 s93, 0x8600000
	s_cselect_b32 s93, 0x6e00000, s93
	s_add_u32 s26, s26, s93
	s_addc_u32 s27, s27, 0
	v_cvt_pk_bf16_f32 v16, v16, v17
	v_cvt_pk_bf16_f32 v17, v18, v19
	global_store_dwordx2 v3, v[16:17], s[26:27]
	v_cvt_pk_bf16_f32 v20, v20, v21
	v_cvt_pk_bf16_f32 v21, v22, v23
	global_store_dwordx2 v3, v[20:21], s[26:27] offset:512
	v_cvt_pk_bf16_f32 v24, v24, v25
	v_cvt_pk_bf16_f32 v25, v26, v27
	global_store_dwordx2 v3, v[24:25], s[26:27] offset:1024
	v_cvt_pk_bf16_f32 v28, v28, v29
	v_cvt_pk_bf16_f32 v29, v30, v31
	global_store_dwordx2 v3, v[28:29], s[26:27] offset:1536
	s_mov_b32 s87, s88
	s_add_u32 s88, s87, s34
	s_cmp_ge_u32 s88, 0x2000
	s_cbranch_scc1 .Lp0_cache_last1
	s_cmp_lt_u32 s88, 0x1000
	s_cselect_b32 s20, s56, s58
	s_cselect_b32 s21, s57, s59
	s_and_b32 s92, s88, 0xfff
	s_lshl_b32 s92, s92, 12
	s_add_u32 s20, s20, s92
	s_addc_u32 s21, s21, 0
	s_mov_b32 s24, s88
	global_load_dwordx4 v[16:19], v2, s[20:21]
	global_load_dwordx4 v[20:23], v2, s[20:21] offset:1024
	global_load_dwordx4 v[24:27], v2, s[20:21] offset:2048
	global_load_dwordx4 v[28:31], v2, s[20:21] offset:3072
	s_waitcnt vmcnt(4)
	s_and_b32 s92, s25, 0xfff
	s_add_u32 s92, s92, 0x2000
	s_lshl_b32 s92, s92, 11
	s_add_u32 s26, s38, s92
	s_addc_u32 s27, s39, 0
	s_cmp_lt_u32 s25, 0x1000
	s_mov_b32 s93, 0x8600000
	s_cselect_b32 s93, 0x6e00000, s93
	s_add_u32 s26, s26, s93
	s_addc_u32 s27, s27, 0
	v_cvt_pk_bf16_f32 v32, v32, v33
	v_cvt_pk_bf16_f32 v33, v34, v35
	global_store_dwordx2 v3, v[32:33], s[26:27]
	v_cvt_pk_bf16_f32 v36, v36, v37
	v_cvt_pk_bf16_f32 v37, v38, v39
	global_store_dwordx2 v3, v[36:37], s[26:27] offset:512
	v_cvt_pk_bf16_f32 v40, v40, v41
	v_cvt_pk_bf16_f32 v41, v42, v43
	global_store_dwordx2 v3, v[40:41], s[26:27] offset:1024
	v_cvt_pk_bf16_f32 v44, v44, v45
	v_cvt_pk_bf16_f32 v45, v46, v47
	global_store_dwordx2 v3, v[44:45], s[26:27] offset:1536
	s_mov_b32 s87, s88
	s_branch .Lp0_cache_loop
.Lp0_cache_last0:
	s_waitcnt vmcnt(0)
	s_and_b32 s92, s24, 0xfff
	s_add_u32 s92, s92, 0x2000
	s_lshl_b32 s92, s92, 11
	s_add_u32 s26, s38, s92
	s_addc_u32 s27, s39, 0
	s_cmp_lt_u32 s24, 0x1000
	s_mov_b32 s93, 0x8600000
	s_cselect_b32 s93, 0x6e00000, s93
	s_add_u32 s26, s26, s93
	s_addc_u32 s27, s27, 0
	v_cvt_pk_bf16_f32 v16, v16, v17
	v_cvt_pk_bf16_f32 v17, v18, v19
	global_store_dwordx2 v3, v[16:17], s[26:27]
	v_cvt_pk_bf16_f32 v20, v20, v21
	v_cvt_pk_bf16_f32 v21, v22, v23
	global_store_dwordx2 v3, v[20:21], s[26:27] offset:512
	v_cvt_pk_bf16_f32 v24, v24, v25
	v_cvt_pk_bf16_f32 v25, v26, v27
	global_store_dwordx2 v3, v[24:25], s[26:27] offset:1024
	v_cvt_pk_bf16_f32 v28, v28, v29
	v_cvt_pk_bf16_f32 v29, v30, v31
	global_store_dwordx2 v3, v[28:29], s[26:27] offset:1536
	s_branch .Lp0_cache_done
.Lp0_cache_last1:
	s_waitcnt vmcnt(0)
	s_and_b32 s92, s25, 0xfff
	s_add_u32 s92, s92, 0x2000
	s_lshl_b32 s92, s92, 11
	s_add_u32 s26, s38, s92
	s_addc_u32 s27, s39, 0
	s_cmp_lt_u32 s25, 0x1000
	s_mov_b32 s93, 0x8600000
	s_cselect_b32 s93, 0x6e00000, s93
	s_add_u32 s26, s26, s93
	s_addc_u32 s27, s27, 0
	v_cvt_pk_bf16_f32 v32, v32, v33
	v_cvt_pk_bf16_f32 v33, v34, v35
	global_store_dwordx2 v3, v[32:33], s[26:27]
	v_cvt_pk_bf16_f32 v36, v36, v37
	v_cvt_pk_bf16_f32 v37, v38, v39
	global_store_dwordx2 v3, v[36:37], s[26:27] offset:512
	v_cvt_pk_bf16_f32 v40, v40, v41
	v_cvt_pk_bf16_f32 v41, v42, v43
	global_store_dwordx2 v3, v[40:41], s[26:27] offset:1024
	v_cvt_pk_bf16_f32 v44, v44, v45
	v_cvt_pk_bf16_f32 v45, v46, v47
	global_store_dwordx2 v3, v[44:45], s[26:27] offset:1536
.Lp0_cache_done:
.LBB0_165:
	v_lshrrev_b32_e32 v1, 20, v0
	v_lshrrev_b32_e32 v0, 10, v0
	s_waitcnt vmcnt(0) lgkmcnt(0)
	v_or_b32_e32 v0, v0, v1
	s_movk_i32 s3, 0x3ff
	v_and_or_b32 v0, v0, s3, v206
	v_cmp_eq_u32_e32 vcc, 0, v0
	s_barrier
	s_barrier
	s_and_saveexec_b64 s[6:7], vcc
	s_cbranch_execz .LBB0_175
	buffer_wbl2 sc1
	s_waitcnt vmcnt(0)
	s_load_dwordx2 s[8:9], s[40:41], 0x58
	v_mov_b32_e32 v2, 0
	s_mov_b64 s[10:11], exec
	v_mbcnt_lo_u32_b32 v1, s10, 0
	v_mbcnt_hi_u32_b32 v1, s11, v1
	s_waitcnt lgkmcnt(0)
	global_load_dword v0, v2, s[8:9] offset:40
	v_cmp_eq_u32_e32 vcc, 0, v1
	s_and_saveexec_b64 s[12:13], vcc
	s_cbranch_execz .LBB0_168
	s_bcnt1_i32_b64 s3, s[10:11]
	v_mov_b32_e32 v3, s3
	global_atomic_add v3, v2, v3, s[8:9] offset:32 sc0

.LBB0_1596:
	s_or_b64 exec, exec, s[2:3]
	s_waitcnt lgkmcnt(0)
	s_barrier
	s_nop 0
	v_lshrrev_b32_e32 v8, 6, v206
	v_and_b32_e32 v1, 63, v206
	s_load_dwordx2 s[88:89], s[0:1], 0x108
	v_readfirstlane_b32 s86, v8
	v_lshlrev_b32_e32 v2, 4, v1
	v_xor_b32_e32 v3, 1, v1
	v_lshlrev_b32_e32 v3, 2, v3
	v_xor_b32_e32 v4, 2, v1
	v_lshlrev_b32_e32 v4, 2, v4
	v_xor_b32_e32 v5, 4, v1
	v_lshlrev_b32_e32 v5, 2, v5
	v_xor_b32_e32 v6, 8, v1
	v_lshlrev_b32_e32 v6, 2, v6
	v_and_b32_e32 v7, 15, v1
	v_lshlrev_b32_e32 v7, 2, v7
	v_mov_b32_e32 v9, 0x358637bd
	s_add_u32 s87, s33, s86
	s_waitcnt lgkmcnt(0)
	global_load_dwordx4 v[16:19], v2, s[88:89]
	global_load_dwordx4 v[20:23], v2, s[88:89] offset:1024
	global_load_dwordx4 v[24:27], v2, s[88:89] offset:2048
	global_load_dwordx4 v[28:31], v2, s[88:89] offset:3072
	s_cmp_ge_u32 s87, 0x10100
	s_cbranch_scc1 .Lfn_done
	s_lshl_b32 s32, s87, 12
	s_add_u32 s90, s36, s32
	s_addc_u32 s91, s37, 0
	s_lshl_b32 s32, s87, 6
	s_add_u32 s94, s38, s32
	s_addc_u32 s95, s39, 0
	s_add_u32 s94, s94, 0x5500000
	s_addc_u32 s95, s95, 0
	global_load_dword v10, v7, s[94:95]
	global_load_dwordx4 v[32:35], v2, s[90:91]
	global_load_dwordx4 v[36:39], v2, s[90:91] offset:1024
	global_load_dwordx4 v[40:43], v2, s[90:91] offset:2048
	global_load_dwordx4 v[44:47], v2, s[90:91] offset:3072
.Lfn_loop:
	s_add_u32 s100, s87, s34
	s_cmp_ge_u32 s100, 0x10100
	s_cbranch_scc1 .Lfn_last0
	s_lshl_b32 s32, s100, 12
	s_add_u32 s92, s36, s32
	s_addc_u32 s93, s37, 0
	s_lshl_b32 s32, s100, 6
	s_add_u32 s94, s38, s32
	s_addc_u32 s95, s39, 0
	s_add_u32 s94, s94, 0x5500000
	s_addc_u32 s95, s95, 0
	global_load_dword v11, v7, s[94:95]
	global_load_dwordx4 v[48:51], v2, s[92:93]
	global_load_dwordx4 v[52:55], v2, s[92:93] offset:1024
	global_load_dwordx4 v[56:59], v2, s[92:93] offset:2048
	global_load_dwordx4 v[60:63], v2, s[92:93] offset:3072
	s_waitcnt vmcnt(5)
	ds_bpermute_b32 v8, v3, v10
	s_waitcnt lgkmcnt(0)
	v_add_f32_e32 v10, v10, v8
	s_nop 0
	ds_bpermute_b32 v8, v4, v10
	s_waitcnt lgkmcnt(0)
	v_add_f32_e32 v10, v10, v8
	s_nop 0
	ds_bpermute_b32 v8, v5, v10
	s_waitcnt lgkmcnt(0)
	v_add_f32_e32 v10, v10, v8
	s_nop 0
	ds_bpermute_b32 v8, v6, v10
	s_waitcnt lgkmcnt(0)
	v_add_f32_e32 v10, v10, v8
	s_nop 0
	s_mov_b32 s32, 0x3a800000
	v_fma_f32 v10, v10, s32, v9
	v_rsq_f32_e32 v10, v10
	s_nop 0
	v_mul_f32_e32 v32, v32, v10
	v_mul_f32_e32 v33, v33, v10
	v_mul_f32_e32 v34, v34, v10
	v_mul_f32_e32 v35, v35, v10
	v_mul_f32_e32 v32, v32, v16
	v_mul_f32_e32 v33, v33, v17
	v_mul_f32_e32 v34, v34, v18
	v_mul_f32_e32 v35, v35, v19
	global_store_dwordx4 v2, v[32:35], s[90:91]
	v_mul_f32_e32 v36, v36, v10
	v_mul_f32_e32 v37, v37, v10
	v_mul_f32_e32 v38, v38, v10
	v_mul_f32_e32 v39, v39, v10
	v_mul_f32_e32 v36, v36, v20
	v_mul_f32_e32 v37, v37, v21
	v_mul_f32_e32 v38, v38, v22
	v_mul_f32_e32 v39, v39, v23
	global_store_dwordx4 v2, v[36:39], s[90:91] offset:1024
	v_mul_f32_e32 v40, v40, v10
	v_mul_f32_e32 v41, v41, v10
	v_mul_f32_e32 v42, v42, v10
	v_mul_f32_e32 v43, v43, v10
	v_mul_f32_e32 v40, v40, v24
	v_mul_f32_e32 v41, v41, v25
	v_mul_f32_e32 v42, v42, v26
	v_mul_f32_e32 v43, v43, v27
	global_store_dwordx4 v2, v[40:43], s[90:91] offset:2048
	v_mul_f32_e32 v44, v44, v10
	v_mul_f32_e32 v45, v45, v10
	v_mul_f32_e32 v46, v46, v10
	v_mul_f32_e32 v47, v47, v10
	v_mul_f32_e32 v44, v44, v28
	v_mul_f32_e32 v45, v45, v29
	v_mul_f32_e32 v46, v46, v30
	v_mul_f32_e32 v47, v47, v31
	global_store_dwordx4 v2, v[44:47], s[90:91] offset:3072
	s_mov_b32 s87, s100
	s_add_u32 s100, s87, s34
	s_cmp_ge_u32 s100, 0x10100
	s_cbranch_scc1 .Lfn_last1
	s_lshl_b32 s32, s100, 12
	s_add_u32 s90, s36, s32
	s_addc_u32 s91, s37, 0
	s_lshl_b32 s32, s100, 6
	s_add_u32 s94, s38, s32
	s_addc_u32 s95, s39, 0
	s_add_u32 s94, s94, 0x5500000
	s_addc_u32 s95, s95, 0
	global_load_dword v10, v7, s[94:95]
	global_load_dwordx4 v[32:35], v2, s[90:91]
	global_load_dwordx4 v[36:39], v2, s[90:91] offset:1024
	global_load_dwordx4 v[40:43], v2, s[90:91] offset:2048
	global_load_dwordx4 v[44:47], v2, s[90:91] offset:3072
	s_waitcnt vmcnt(5)
	ds_bpermute_b32 v8, v3, v11
	s_waitcnt lgkmcnt(0)
	v_add_f32_e32 v11, v11, v8
	s_nop 0
	ds_bpermute_b32 v8, v4, v11
	s_waitcnt lgkmcnt(0)
	v_add_f32_e32 v11, v11, v8
	s_nop 0
	ds_bpermute_b32 v8, v5, v11
	s_waitcnt lgkmcnt(0)
	v_add_f32_e32 v11, v11, v8
	s_nop 0
	ds_bpermute_b32 v8, v6, v11
	s_waitcnt lgkmcnt(0)
	v_add_f32_e32 v11, v11, v8
	s_nop 0
	s_mov_b32 s32, 0x3a800000
	v_fma_f32 v11, v11, s32, v9
	v_rsq_f32_e32 v11, v11
	s_nop 0
	v_mul_f32_e32 v48, v48, v11
	v_mul_f32_e32 v49, v49, v11
	v_mul_f32_e32 v50, v50, v11
	v_mul_f32_e32 v51, v51, v11
	v_mul_f32_e32 v48, v48, v16
	v_mul_f32_e32 v49, v49, v17
	v_mul_f32_e32 v50, v50, v18
	v_mul_f32_e32 v51, v51, v19
	global_store_dwordx4 v2, v[48:51], s[92:93]
	v_mul_f32_e32 v52, v52, v11
	v_mul_f32_e32 v53, v53, v11
	v_mul_f32_e32 v54, v54, v11
	v_mul_f32_e32 v55, v55, v11
	v_mul_f32_e32 v52, v52, v20
	v_mul_f32_e32 v53, v53, v21
	v_mul_f32_e32 v54, v54, v22
	v_mul_f32_e32 v55, v55, v23
	global_store_dwordx4 v2, v[52:55], s[92:93] offset:1024
	v_mul_f32_e32 v56, v56, v11
	v_mul_f32_e32 v57, v57, v11
	v_mul_f32_e32 v58, v58, v11
	v_mul_f32_e32 v59, v59, v11
	v_mul_f32_e32 v56, v56, v24
	v_mul_f32_e32 v57, v57, v25
	v_mul_f32_e32 v58, v58, v26
	v_mul_f32_e32 v59, v59, v27
	global_store_dwordx4 v2, v[56:59], s[92:93] offset:2048
	v_mul_f32_e32 v60, v60, v11
	v_mul_f32_e32 v61, v61, v11
	v_mul_f32_e32 v62, v62, v11
	v_mul_f32_e32 v63, v63, v11
	v_mul_f32_e32 v60, v60, v28
	v_mul_f32_e32 v61, v61, v29
	v_mul_f32_e32 v62, v62, v30
	v_mul_f32_e32 v63, v63, v31
	global_store_dwordx4 v2, v[60:63], s[92:93] offset:3072
	s_mov_b32 s87, s100
	s_branch .Lfn_loop
.Lfn_last0:
	s_waitcnt vmcnt(0)
	ds_bpermute_b32 v8, v3, v10
	s_waitcnt lgkmcnt(0)
	v_add_f32_e32 v10, v10, v8
	s_nop 0
	ds_bpermute_b32 v8, v4, v10
	s_waitcnt lgkmcnt(0)
	v_add_f32_e32 v10, v10, v8
	s_nop 0
	ds_bpermute_b32 v8, v5, v10
	s_waitcnt lgkmcnt(0)
	v_add_f32_e32 v10, v10, v8
	s_nop 0
	ds_bpermute_b32 v8, v6, v10
	s_waitcnt lgkmcnt(0)
	v_add_f32_e32 v10, v10, v8
	s_nop 0
	s_mov_b32 s32, 0x3a800000
	v_fma_f32 v10, v10, s32, v9
	v_rsq_f32_e32 v10, v10
	s_nop 0
	v_mul_f32_e32 v32, v32, v10
	v_mul_f32_e32 v33, v33, v10
	v_mul_f32_e32 v34, v34, v10
	v_mul_f32_e32 v35, v35, v10
	v_mul_f32_e32 v32, v32, v16
	v_mul_f32_e32 v33, v33, v17
	v_mul_f32_e32 v34, v34, v18
	v_mul_f32_e32 v35, v35, v19
	global_store_dwordx4 v2, v[32:35], s[90:91]
	v_mul_f32_e32 v36, v36, v10
	v_mul_f32_e32 v37, v37, v10
	v_mul_f32_e32 v38, v38, v10
	v_mul_f32_e32 v39, v39, v10
	v_mul_f32_e32 v36, v36, v20
	v_mul_f32_e32 v37, v37, v21
	v_mul_f32_e32 v38, v38, v22
	v_mul_f32_e32 v39, v39, v23
	global_store_dwordx4 v2, v[36:39], s[90:91] offset:1024
	v_mul_f32_e32 v40, v40, v10
	v_mul_f32_e32 v41, v41, v10
	v_mul_f32_e32 v42, v42, v10
	v_mul_f32_e32 v43, v43, v10
	v_mul_f32_e32 v40, v40, v24
	v_mul_f32_e32 v41, v41, v25
	v_mul_f32_e32 v42, v42, v26
	v_mul_f32_e32 v43, v43, v27
	global_store_dwordx4 v2, v[40:43], s[90:91] offset:2048
	v_mul_f32_e32 v44, v44, v10
	v_mul_f32_e32 v45, v45, v10
	v_mul_f32_e32 v46, v46, v10
	v_mul_f32_e32 v47, v47, v10
	v_mul_f32_e32 v44, v44, v28
	v_mul_f32_e32 v45, v45, v29
	v_mul_f32_e32 v46, v46, v30
	v_mul_f32_e32 v47, v47, v31
	global_store_dwordx4 v2, v[44:47], s[90:91] offset:3072
	s_branch .Lfn_done
.Lfn_last1:
	s_waitcnt vmcnt(0)
	ds_bpermute_b32 v8, v3, v11
	s_waitcnt lgkmcnt(0)
	v_add_f32_e32 v11, v11, v8
	s_nop 0
	ds_bpermute_b32 v8, v4, v11
	s_waitcnt lgkmcnt(0)
	v_add_f32_e32 v11, v11, v8
	s_nop 0
	ds_bpermute_b32 v8, v5, v11
	s_waitcnt lgkmcnt(0)
	v_add_f32_e32 v11, v11, v8
	s_nop 0
	ds_bpermute_b32 v8, v6, v11
	s_waitcnt lgkmcnt(0)
	v_add_f32_e32 v11, v11, v8
	s_nop 0
	s_mov_b32 s32, 0x3a800000
	v_fma_f32 v11, v11, s32, v9
	v_rsq_f32_e32 v11, v11
	s_nop 0
	v_mul_f32_e32 v48, v48, v11
	v_mul_f32_e32 v49, v49, v11
	v_mul_f32_e32 v50, v50, v11
	v_mul_f32_e32 v51, v51, v11
	v_mul_f32_e32 v48, v48, v16
	v_mul_f32_e32 v49, v49, v17
	v_mul_f32_e32 v50, v50, v18
	v_mul_f32_e32 v51, v51, v19
	global_store_dwordx4 v2, v[48:51], s[92:93]
	v_mul_f32_e32 v52, v52, v11
	v_mul_f32_e32 v53, v53, v11
	v_mul_f32_e32 v54, v54, v11
	v_mul_f32_e32 v55, v55, v11
	v_mul_f32_e32 v52, v52, v20
	v_mul_f32_e32 v53, v53, v21
	v_mul_f32_e32 v54, v54, v22
	v_mul_f32_e32 v55, v55, v23
	global_store_dwordx4 v2, v[52:55], s[92:93] offset:1024
	v_mul_f32_e32 v56, v56, v11
	v_mul_f32_e32 v57, v57, v11
	v_mul_f32_e32 v58, v58, v11
	v_mul_f32_e32 v59, v59, v11
	v_mul_f32_e32 v56, v56, v24
	v_mul_f32_e32 v57, v57, v25
	v_mul_f32_e32 v58, v58, v26
	v_mul_f32_e32 v59, v59, v27
	global_store_dwordx4 v2, v[56:59], s[92:93] offset:2048
	v_mul_f32_e32 v60, v60, v11
	v_mul_f32_e32 v61, v61, v11
	v_mul_f32_e32 v62, v62, v11
	v_mul_f32_e32 v63, v63, v11
	v_mul_f32_e32 v60, v60, v28
	v_mul_f32_e32 v61, v61, v29
	v_mul_f32_e32 v62, v62, v30
	v_mul_f32_e32 v63, v63, v31
	global_store_dwordx4 v2, v[60:63], s[92:93] offset:3072
.Lfn_done:
.LBB0_1599:
	s_endpgm
